# cache-policy hints: nt on the read-once f32 weight / x loads of P0 and on the write-once f32 output stores of P10 (v47 otherwise)
# speedup vs baseline: 1.0032x; 1.0032x over previous
; #define KOUT() ((float*)karg_u64<128>())
; template <bool UPMAP = false>
; __device__ __forceinline__ void transpose_item(const float* W, int K, int N, bf16* WT, int ldk, int row_off, LAS float* scr, int item, int lane, const float* kscale = nullptr) {
;     const int nblk = N / 32, kb = item / nblk, nb = item % nblk, k0 = 64 * kb, n0 = 32 * nb;
;     const int drow0 = UPMAP ? (n0 < DFF ? (n0 >> 7) * 256 + (n0 & 127) : ((n0 - DFF) >> 7) * 256 + 128 + ((n0 - DFF) & 127)) : row_off + n0;
;     f32x4 wv[8]; const int kr = lane >> 3, nq = (lane & 7) * 4;
; #pragma unroll
;     for (int i = 0; i < 8; ++i) wv[i] = *(const GAS f32x4*)(W + (size_t)(k0 + 8 * i + kr) * N + n0 + nq);
; #pragma unroll
;     for (int i = 0; i < 8; ++i) { const int kk = 8 * i + kr; f32x4 w = wv[i]; if (kscale) w = w * kscale[k0 + kk];
;         LAS float* d = scr + kk * 33 + nq; d[0] = w.x; d[1] = w.y; d[2] = w.z; d[3] = w.w; }
;     LDS_WAIT(); asm volatile("" ::: "memory");
;     const int c = lane & 7;
; #pragma unroll
;     for (int j = 0; j < 4; ++j) { const int n = (lane >> 3) + 8 * j; const LAS float* s = scr + (8 * c) * 33 + n;
;         v4u o; o.x = pk2(s[0 * 33], s[1 * 33]); o.y = pk2(s[2 * 33], s[3 * 33]); o.z = pk2(s[4 * 33], s[5 * 33]); o.w = pk2(s[6 * 33], s[7 * 33]);
;         *(GAS v4u*)(WT + (size_t)(drow0 + n) * ldk + k0 + 8 * c) = o; }
;     LDS_WAIT(); asm volatile("" ::: "memory");
; }
; __global__ void __launch_bounds__(NWAVES * 64, 2) fwd_kernel(Args args) {
;     ...
;         for (int it = gw; it < NITEMS; it += NGW) {
;             int r = it;
;             if (r < I_IN) { transpose_item_in(KIN(3), (bf16*)(ws + WS_WIN), ws + WS_WIN8, scr, r, lane); continue; } r -= I_IN;
;             if (r < I_ATT) { transpose_item_f8(KIN(6), NQ, DM, ws + WS_WATT, NQ, scr, r, lane); continue; } r -= I_ATT;
;             if (r < 4 * I_POOL) { const int g = r / I_POOL; transpose_item(KIN(7) + (size_t)g * 512 * 1024, 512, 1024, (bf16*)(ws + WS_WPOOL), 512, g * 1024, scr, r % I_POOL, lane); continue; } r -= 4 * I_POOL;
;             if (r < I_OUT) { transpose_item(KIN(9), DM, DM, (bf16*)(ws + WS_WOUT), DM, 0, scr, r, lane); continue; } r -= I_OUT;
;             if (r < I_UP) { transpose_item<true>(KIN(11), DM, NUP, (bf16*)(ws + WS_WUP), DM, 0, scr, r, lane, KIN(10)); continue; } r -= I_UP;
;             transpose_item(KIN(14), DFF, DM, (bf16*)KOUT(), DFF, 0, scr, I_DOWN_TAIL + r, lane);
.LBB0_16:
	s_cmpk_gt_i32 s38, 0x67ff
	s_mov_b64 s[4:5], -1
	s_cbranch_scc0 .LBB0_50
	s_cmpk_gt_u32 s38, 0x77ff
	s_cbranch_scc0 .LBB0_47
	s_cmpk_gt_u32 s38, 0x7bff
	s_cbranch_scc0 .LBB0_44
	s_cmpk_gt_u32 s38, 0x9bff
	s_cbranch_scc0 .LBB0_41
	s_cmp_gt_u32 s38, 0x147ff
	s_cbranch_scc0 .LBB0_22
	s_add_i32 s6, s38, 0xe000
	s_lshr_b32 s6, s6, 1
	s_and_b32 s14, s6, 0x7fc0
	s_and_b32 s6, s11, 0xfe0
	s_load_dwordx2 s[8:9], s[0:1], 0x70
	s_waitcnt lgkmcnt(0)
	s_lshl_b32 s15, s6, 2
	s_add_u32 s8, s8, s15
	v_or_b32_e32 v4, s14, v39
	s_addc_u32 s9, s9, 0
	s_waitcnt lgkmcnt(0)
	v_lshl_add_u64 v[2:3], s[8:9], 0, v[40:41]
	v_lshlrev_b32_e32 v4, 14, v4
	v_mov_b32_e32 v5, v41
	v_lshl_add_u64 v[30:31], v[2:3], 0, v[4:5]
	v_add_co_u32_e32 v10, vcc, s19, v30
	s_load_dwordx2 s[4:5], s[0:1], 0x80
	s_waitcnt lgkmcnt(0)
	s_lshl_b32 s8, s14, 1
	s_nop 0
	v_addc_co_u32_e32 v11, vcc, 0, v31, vcc
	global_load_dwordx4 v[2:5], v[30:31], off nt
	global_load_dwordx4 v[6:9], v[10:11], off nt
	v_add_co_u32_e32 v10, vcc, s20, v30
	v_or_b32_e32 v34, s6, v39
	s_nop 0
	v_addc_co_u32_e32 v11, vcc, 0, v31, vcc
	v_add_co_u32_e32 v14, vcc, s21, v30
	s_add_u32 s4, s4, s8
	s_nop 0
	v_addc_co_u32_e32 v15, vcc, 0, v31, vcc
	v_add_co_u32_e32 v18, vcc, s22, v30
	global_load_dwordx4 v[10:13], v[10:11], off nt
	s_nop 0
	global_load_dwordx4 v[14:17], v[14:15], off nt
	v_addc_co_u32_e32 v19, vcc, 0, v31, vcc
	v_add_co_u32_e32 v22, vcc, s23, v30
	v_mov_b32_e32 v55, v41
	s_nop 0
	v_addc_co_u32_e32 v23, vcc, 0, v31, vcc
	global_load_dwordx4 v[18:21], v[18:19], off nt
	s_nop 0
	global_load_dwordx4 v[22:25], v[22:23], off nt
	v_add_co_u32_e32 v26, vcc, s24, v30
	v_mul_u32_u24_e32 v34, 0x2b00, v34
	s_nop 0
	v_addc_co_u32_e32 v27, vcc, 0, v31, vcc
	global_load_dwordx4 v[26:29], v[26:27], off nt
	v_add_co_u32_e32 v30, vcc, s25, v30
	s_addc_u32 s5, s5, 0
	s_nop 0
	v_addc_co_u32_e32 v31, vcc, 0, v31, vcc
	global_load_dwordx4 v[30:33], v[30:31], off nt
	v_mov_b32_e32 v35, v41
	v_lshlrev_b32_e32 v34, 1, v34
	v_lshl_add_u64 v[56:57], s[4:5], 0, v[54:55]
	v_or_b32_e32 v36, s6, v58
	v_mul_u32_u24_e32 v36, 0x2b00, v36
	v_mov_b32_e32 v37, v41
	v_lshlrev_b32_e32 v36, 1, v36
	s_mov_b64 s[4:5], 0
	s_waitcnt vmcnt(0)
	ds_write2_b32 v62, v2, v3 offset1:1
	ds_write2_b32 v62, v4, v5 offset0:2 offset1:3
	ds_write2_b32 v63, v6, v7 offset1:1
	ds_write2_b32 v64, v8, v9 offset1:1
	ds_write2_b32 v65, v10, v11 offset1:1
	ds_write2_b32 v66, v12, v13 offset1:1
	ds_write2_b32 v67, v14, v15 offset1:1
	ds_write2_b32 v68, v16, v17 offset1:1
	ds_write2_b32 v69, v18, v19 offset1:1
	ds_write2_b32 v70, v20, v21 offset1:1
	ds_write2_b32 v71, v22, v23 offset1:1
	ds_write2_b32 v72, v24, v25 offset1:1
	ds_write2_b32 v73, v26, v27 offset1:1
	ds_write2_b32 v74, v28, v29 offset1:1
	ds_write2_b32 v75, v30, v31 offset1:1
	ds_write2_b32 v76, v32, v33 offset1:1
	s_waitcnt lgkmcnt(0)
	ds_read2_b32 v[6:7], v61 offset0:33 offset1:41
	ds_read2_b32 v[8:9], v61 offset1:8
	ds_read2_b32 v[10:11], v61 offset0:66 offset1:74
	ds_read2_b32 v[12:13], v61 offset0:99 offset1:107
	ds_read2_b32 v[14:15], v61 offset0:132 offset1:140
	ds_read2_b32 v[16:17], v61 offset0:165 offset1:173
	ds_read2_b32 v[18:19], v61 offset0:198 offset1:206
	ds_read2_b32 v[20:21], v61 offset0:231 offset1:239
	v_lshl_add_u64 v[22:23], v[56:57], 0, v[34:35]
	s_waitcnt lgkmcnt(0)
	v_cvt_pk_bf16_f32 v2, v8, v6
	v_cvt_pk_bf16_f32 v3, v10, v12
	v_cvt_pk_bf16_f32 v4, v14, v16
	v_cvt_pk_bf16_f32 v5, v18, v20
	global_store_dwordx4 v[22:23], v[2:5], off
	v_cvt_pk_bf16_f32 v6, v9, v7
	v_cvt_pk_bf16_f32 v7, v11, v13
	v_cvt_pk_bf16_f32 v8, v15, v17
	v_cvt_pk_bf16_f32 v9, v19, v21
	ds_read2_b32 v[10:11], v61 offset0:16 offset1:24
	ds_read2_b32 v[12:13], v61 offset0:49 offset1:57
	ds_read2_b32 v[14:15], v61 offset0:82 offset1:90
	ds_read2_b32 v[16:17], v61 offset0:115 offset1:123
	ds_read2_b32 v[18:19], v61 offset0:148 offset1:156
	ds_read2_b32 v[20:21], v61 offset0:181 offset1:189
	ds_read2_b32 v[22:23], v61 offset0:214 offset1:222
	ds_read2_b32 v[24:25], v61 offset0:247 offset1:255
	v_lshl_add_u64 v[2:3], v[56:57], 0, v[36:37]
	global_store_dwordx4 v[2:3], v[6:9], off
	s_waitcnt lgkmcnt(6)
	v_cvt_pk_bf16_f32 v2, v10, v12
	s_waitcnt lgkmcnt(4)
	v_cvt_pk_bf16_f32 v3, v14, v16
	v_or_b32_e32 v6, s6, v59
	v_mul_u32_u24_e32 v6, 0x2b00, v6
	v_lshlrev_b32_e32 v6, 1, v6
	v_mov_b32_e32 v7, v41
	s_waitcnt lgkmcnt(2)
	v_cvt_pk_bf16_f32 v4, v18, v20
	s_waitcnt lgkmcnt(0)
	v_cvt_pk_bf16_f32 v5, v22, v24
	v_lshl_add_u64 v[6:7], v[56:57], 0, v[6:7]
	global_store_dwordx4 v[6:7], v[2:5], off
	v_or_b32_e32 v6, s6, v60
	v_mul_u32_u24_e32 v6, 0x2b00, v6
	v_lshlrev_b32_e32 v6, 1, v6
	v_mov_b32_e32 v7, v41
	v_cvt_pk_bf16_f32 v2, v11, v13
	v_cvt_pk_bf16_f32 v3, v15, v17
	v_cvt_pk_bf16_f32 v4, v19, v21
	v_cvt_pk_bf16_f32 v5, v23, v25
	v_lshl_add_u64 v[6:7], v[56:57], 0, v[6:7]
	global_store_dwordx4 v[6:7], v[2:5], off
	s_waitcnt lgkmcnt(0)

; #define GAS __attribute__((address_space(1)))
; #define LAS __attribute__((address_space(3)))
; template <bool UPMAP = false>
; __device__ __forceinline__ void transpose_item(const float* W, int K, int N, bf16* WT, int ldk, int row_off, LAS float* scr, int item, int lane, const float* kscale = nullptr) {
;     const int nblk = N / 32, kb = item / nblk, nb = item % nblk, k0 = 64 * kb, n0 = 32 * nb;
;     const int drow0 = UPMAP ? (n0 < DFF ? (n0 >> 7) * 256 + (n0 & 127) : ((n0 - DFF) >> 7) * 256 + 128 + ((n0 - DFF) & 127)) : row_off + n0;
;     f32x4 wv[8]; const int kr = lane >> 3, nq = (lane & 7) * 4;
; #pragma unroll
;     for (int i = 0; i < 8; ++i) wv[i] = *(const GAS f32x4*)(W + (size_t)(k0 + 8 * i + kr) * N + n0 + nq);
; #pragma unroll
;     for (int i = 0; i < 8; ++i) { const int kk = 8 * i + kr; f32x4 w = wv[i]; if (kscale) w = w * kscale[k0 + kk];
;         LAS float* d = scr + kk * 33 + nq; d[0] = w.x; d[1] = w.y; d[2] = w.z; d[3] = w.w; }
; __global__ void __launch_bounds__(NWAVES * 64, 2) fwd_kernel(Args args) {
;     ...
;             if (r < I_UP) { transpose_item<true>(KIN(11), DM, NUP, (bf16*)(ws + WS_WUP), DM, 0, scr, r, lane, KIN(10)); continue; } r -= I_UP;
.LBB0_27:
	s_lshl_b32 s6, s6, 6
	s_and_b32 s6, s6, 0x1fc0
	s_lshl_b32 s14, s40, 2
	v_or_b32_e32 v34, s6, v39
	s_add_u32 s4, s4, s14
	s_addc_u32 s5, s5, 0
	v_mul_u32_u24_e32 v4, 0x5600, v34
	s_waitcnt lgkmcnt(0)
	v_lshl_add_u64 v[2:3], s[4:5], 0, v[40:41]
	v_lshlrev_b32_e32 v4, 2, v4
	v_mov_b32_e32 v5, v41
	v_lshl_add_u64 v[2:3], v[2:3], 0, v[4:5]
	v_add_co_u32_e32 v4, vcc, s26, v2
	s_cmp_lg_u64 s[8:9], 0
	s_nop 0
	v_addc_co_u32_e32 v5, vcc, 0, v3, vcc
	global_load_dwordx4 v[26:29], v[2:3], off nt
	global_load_dwordx4 v[30:33], v[4:5], off nt
	v_add_co_u32_e32 v4, vcc, s27, v2
	s_cselect_b64 s[14:15], -1, 0
	s_nop 0
	v_addc_co_u32_e32 v5, vcc, 0, v3, vcc
	v_add_co_u32_e32 v6, vcc, s28, v2
	s_cmp_eq_u64 s[8:9], 0
	s_nop 0
	v_addc_co_u32_e32 v7, vcc, 0, v3, vcc
	global_load_dwordx4 v[18:21], v[4:5], off nt
	global_load_dwordx4 v[22:25], v[6:7], off nt
	v_add_co_u32_e32 v4, vcc, s29, v2
	v_add_lshl_u32 v56, v39, s6, 2
	s_nop 0
	v_addc_co_u32_e32 v5, vcc, 0, v3, vcc
	v_add_co_u32_e32 v6, vcc, 0x35c000, v2
	s_nop 1
	v_addc_co_u32_e32 v7, vcc, 0, v3, vcc
	global_load_dwordx4 v[10:13], v[4:5], off nt
	global_load_dwordx4 v[14:17], v[6:7], off nt
	v_add_co_u32_e32 v4, vcc, 0x408000, v2
	s_nop 1
	v_addc_co_u32_e32 v5, vcc, 0, v3, vcc
	v_add_co_u32_e32 v6, vcc, 0x4b4000, v2
	s_nop 1
	v_addc_co_u32_e32 v7, vcc, 0, v3, vcc
	global_load_dwordx4 v[2:5], v[4:5], off nt
	s_nop 0
	global_load_dwordx4 v[6:9], v[6:7], off nt
	s_cbranch_scc1 .LBB0_55
	v_lshlrev_b32_e32 v34, 2, v34
	v_mov_b32_e32 v35, v41
	v_lshl_add_u64 v[34:35], s[8:9], 0, v[34:35]
	flat_load_dword v34, v[34:35]
	v_mov_b32_e32 v57, v41
	v_lshl_add_u64 v[36:37], s[8:9], 0, v[56:57]
	s_waitcnt vmcnt(0) lgkmcnt(0)
	v_pk_mul_f32 v[78:79], v[28:29], v[34:35] op_sel_hi:[1,0]
	v_pk_mul_f32 v[34:35], v[26:27], v[34:35] op_sel_hi:[1,0]
	ds_write2_b32 v62, v34, v35 offset1:1
	ds_write2_b32 v62, v78, v79 offset0:2 offset1:3
	flat_load_dword v34, v[36:37] offset:32
	s_waitcnt vmcnt(0) lgkmcnt(0)
	v_pk_mul_f32 v[36:37], v[32:33], v[34:35] op_sel_hi:[1,0]
	v_pk_mul_f32 v[34:35], v[30:31], v[34:35] op_sel_hi:[1,0]
	s_cbranch_execnz .LBB0_30

; #define GAS __attribute__((address_space(1)))
; #define LAS __attribute__((address_space(3)))
; #define LDS_WAIT() asm volatile("s_waitcnt lgkmcnt(0)" ::: "memory")
; __device__ __forceinline__ unsigned pk2(float lo, float hi) { return pg8::cvt_pk_bf16(lo, hi); }
; template <bool UPMAP = false>
; __device__ __forceinline__ void transpose_item(const float* W, int K, int N, bf16* WT, int ldk, int row_off, LAS float* scr, int item, int lane, const float* kscale = nullptr) {
;     const int nblk = N / 32, kb = item / nblk, nb = item % nblk, k0 = 64 * kb, n0 = 32 * nb;
;     const int drow0 = UPMAP ? (n0 < DFF ? (n0 >> 7) * 256 + (n0 & 127) : ((n0 - DFF) >> 7) * 256 + 128 + ((n0 - DFF) & 127)) : row_off + n0;
;     f32x4 wv[8]; const int kr = lane >> 3, nq = (lane & 7) * 4;
; #pragma unroll
;     for (int i = 0; i < 8; ++i) wv[i] = *(const GAS f32x4*)(W + (size_t)(k0 + 8 * i + kr) * N + n0 + nq);
; #pragma unroll
;     for (int i = 0; i < 8; ++i) { const int kk = 8 * i + kr; f32x4 w = wv[i]; if (kscale) w = w * kscale[k0 + kk];
;         LAS float* d = scr + kk * 33 + nq; d[0] = w.x; d[1] = w.y; d[2] = w.z; d[3] = w.w; }
;     LDS_WAIT(); asm volatile("" ::: "memory");
;     const int c = lane & 7;
; #pragma unroll
;     for (int j = 0; j < 4; ++j) { const int n = (lane >> 3) + 8 * j; const LAS float* s = scr + (8 * c) * 33 + n;
;         v4u o; o.x = pk2(s[0 * 33], s[1 * 33]); o.y = pk2(s[2 * 33], s[3 * 33]); o.z = pk2(s[4 * 33], s[5 * 33]); o.w = pk2(s[6 * 33], s[7 * 33]);
;         *(GAS v4u*)(WT + (size_t)(drow0 + n) * ldk + k0 + 8 * c) = o; }
;     LDS_WAIT(); asm volatile("" ::: "memory");
; }
; __global__ void __launch_bounds__(NWAVES * 64, 2) fwd_kernel(Args args) {
;     ...
;             if (r < I_OUT) { transpose_item(KIN(9), DM, DM, (bf16*)(ws + WS_WOUT), DM, 0, scr, r, lane); continue; } r -= I_OUT;
.LBB0_41:
	s_andn2_b64 vcc, exec, s[4:5]
	s_cbranch_vccnz .LBB0_43
	s_add_i32 s6, s38, 0x8400
	s_lshr_b32 s6, s6, 1
	s_and_b32 s8, s11, 0xfe0
	s_load_dwordx2 s[4:5], s[0:1], 0x48
	s_waitcnt lgkmcnt(0)
	s_and_b32 s6, s6, 0x7fc0
	s_lshl_b32 s9, s8, 2
	s_add_u32 s4, s4, s9
	v_or_b32_e32 v4, s6, v39
	s_addc_u32 s5, s5, 0
	s_waitcnt lgkmcnt(0)
	v_lshl_add_u64 v[2:3], s[4:5], 0, v[40:41]
	v_lshlrev_b32_e32 v4, 14, v4
	v_mov_b32_e32 v5, v41
	v_lshl_add_u64 v[30:31], v[2:3], 0, v[4:5]
	v_add_co_u32_e32 v10, vcc, s19, v30
	v_or_b32_e32 v34, s8, v39
	s_nop 0
	v_addc_co_u32_e32 v11, vcc, 0, v31, vcc
	v_add_co_u32_e32 v18, vcc, s20, v30
	global_load_dwordx4 v[2:5], v[30:31], off nt
	global_load_dwordx4 v[6:9], v[10:11], off nt
	v_addc_co_u32_e32 v19, vcc, 0, v31, vcc
	v_add_co_u32_e32 v20, vcc, s21, v30
	s_lshl_b32 s6, s6, 1
	s_nop 0
	v_addc_co_u32_e32 v21, vcc, 0, v31, vcc
	v_add_co_u32_e32 v26, vcc, s22, v30
	global_load_dwordx4 v[10:13], v[18:19], off nt
	global_load_dwordx4 v[14:17], v[20:21], off nt
	v_addc_co_u32_e32 v27, vcc, 0, v31, vcc
	v_add_co_u32_e32 v28, vcc, s23, v30
	v_mov_b32_e32 v35, v41
	s_nop 0
	v_addc_co_u32_e32 v29, vcc, 0, v31, vcc
	global_load_dwordx4 v[18:21], v[26:27], off nt
	global_load_dwordx4 v[22:25], v[28:29], off nt
	v_add_co_u32_e32 v26, vcc, s24, v30
	v_lshlrev_b32_e32 v34, 13, v34
	s_nop 0
	v_addc_co_u32_e32 v27, vcc, 0, v31, vcc
	global_load_dwordx4 v[26:29], v[26:27], off nt
	v_add_co_u32_e32 v30, vcc, s25, v30
	v_lshl_add_u64 v[56:57], v[44:45], 0, s[6:7]
	s_nop 0
	v_addc_co_u32_e32 v31, vcc, 0, v31, vcc
	global_load_dwordx4 v[30:33], v[30:31], off nt
	v_lshl_add_u64 v[34:35], v[56:57], 0, v[34:35]
	v_or_b32_e32 v36, s8, v58
	v_mov_b32_e32 v37, v41
	v_lshlrev_b32_e32 v36, 13, v36
	v_lshl_add_u64 v[36:37], v[56:57], 0, v[36:37]
	s_waitcnt vmcnt(0)
	ds_write2_b32 v62, v2, v3 offset1:1
	ds_write2_b32 v62, v4, v5 offset0:2 offset1:3
	ds_write2_b32 v63, v6, v7 offset1:1
	ds_write2_b32 v64, v8, v9 offset1:1
	ds_write2_b32 v65, v10, v11 offset1:1
	ds_write2_b32 v66, v12, v13 offset1:1
	ds_write2_b32 v67, v14, v15 offset1:1
	ds_write2_b32 v68, v16, v17 offset1:1
	ds_write2_b32 v69, v18, v19 offset1:1
	ds_write2_b32 v70, v20, v21 offset1:1
	ds_write2_b32 v71, v22, v23 offset1:1
	ds_write2_b32 v72, v24, v25 offset1:1
	ds_write2_b32 v73, v26, v27 offset1:1
	ds_write2_b32 v74, v28, v29 offset1:1
	ds_write2_b32 v75, v30, v31 offset1:1
	ds_write2_b32 v76, v32, v33 offset1:1
	s_waitcnt lgkmcnt(0)
	ds_read2_b32 v[6:7], v61 offset0:33 offset1:41
	ds_read2_b32 v[8:9], v61 offset1:8
	ds_read2_b32 v[10:11], v61 offset0:66 offset1:74
	ds_read2_b32 v[12:13], v61 offset0:99 offset1:107
	ds_read2_b32 v[14:15], v61 offset0:132 offset1:140
	ds_read2_b32 v[16:17], v61 offset0:165 offset1:173
	ds_read2_b32 v[18:19], v61 offset0:198 offset1:206
	ds_read2_b32 v[20:21], v61 offset0:231 offset1:239
	ds_read2_b32 v[22:23], v61 offset0:49 offset1:57
	ds_read2_b32 v[24:25], v61 offset0:16 offset1:24
	ds_read2_b32 v[26:27], v61 offset0:82 offset1:90
	ds_read2_b32 v[28:29], v61 offset0:115 offset1:123
	ds_read2_b32 v[30:31], v61 offset0:148 offset1:156
	s_waitcnt lgkmcnt(0)
	v_cvt_pk_bf16_f32 v2, v8, v6
	v_cvt_pk_bf16_f32 v3, v10, v12
	v_cvt_pk_bf16_f32 v4, v14, v16
	v_cvt_pk_bf16_f32 v5, v18, v20
	global_store_dwordx4 v[34:35], v[2:5], off
	v_cvt_pk_bf16_f32 v6, v9, v7
	v_cvt_pk_bf16_f32 v7, v11, v13
	v_cvt_pk_bf16_f32 v8, v15, v17
	ds_read2_b32 v[10:11], v61 offset0:181 offset1:189
	ds_read2_b32 v[12:13], v61 offset0:214 offset1:222
	ds_read2_b32 v[14:15], v61 offset0:247 offset1:255
	v_cvt_pk_bf16_f32 v9, v19, v21
	global_store_dwordx4 v[36:37], v[6:9], off
	v_cvt_pk_bf16_f32 v2, v24, v22
	v_cvt_pk_bf16_f32 v3, v26, v28
	v_or_b32_e32 v6, s8, v59
	v_lshlrev_b32_e32 v6, 13, v6
	v_mov_b32_e32 v7, v41
	s_waitcnt lgkmcnt(2)
	v_cvt_pk_bf16_f32 v4, v30, v10
	s_waitcnt lgkmcnt(0)
	v_cvt_pk_bf16_f32 v5, v12, v14
	v_lshl_add_u64 v[6:7], v[56:57], 0, v[6:7]
	global_store_dwordx4 v[6:7], v[2:5], off
	v_or_b32_e32 v6, s8, v60
	v_lshlrev_b32_e32 v6, 13, v6
	v_mov_b32_e32 v7, v41
	v_cvt_pk_bf16_f32 v2, v25, v23
	v_cvt_pk_bf16_f32 v3, v27, v29
	v_cvt_pk_bf16_f32 v4, v31, v11
	v_cvt_pk_bf16_f32 v5, v13, v15
	v_lshl_add_u64 v[6:7], v[56:57], 0, v[6:7]
	global_store_dwordx4 v[6:7], v[2:5], off
	s_waitcnt lgkmcnt(0)

; #define GAS __attribute__((address_space(1)))
; #define LAS __attribute__((address_space(3)))
; #define LDS_WAIT() asm volatile("s_waitcnt lgkmcnt(0)" ::: "memory")
; __device__ __forceinline__ unsigned pk2(float lo, float hi) { return pg8::cvt_pk_bf16(lo, hi); }
; template <bool UPMAP = false>
; __device__ __forceinline__ void transpose_item(const float* W, int K, int N, bf16* WT, int ldk, int row_off, LAS float* scr, int item, int lane, const float* kscale = nullptr) {
;     const int nblk = N / 32, kb = item / nblk, nb = item % nblk, k0 = 64 * kb, n0 = 32 * nb;
;     const int drow0 = UPMAP ? (n0 < DFF ? (n0 >> 7) * 256 + (n0 & 127) : ((n0 - DFF) >> 7) * 256 + 128 + ((n0 - DFF) & 127)) : row_off + n0;
;     f32x4 wv[8]; const int kr = lane >> 3, nq = (lane & 7) * 4;
; #pragma unroll
;     for (int i = 0; i < 8; ++i) wv[i] = *(const GAS f32x4*)(W + (size_t)(k0 + 8 * i + kr) * N + n0 + nq);
; #pragma unroll
;     for (int i = 0; i < 8; ++i) { const int kk = 8 * i + kr; f32x4 w = wv[i]; if (kscale) w = w * kscale[k0 + kk];
;         LAS float* d = scr + kk * 33 + nq; d[0] = w.x; d[1] = w.y; d[2] = w.z; d[3] = w.w; }
;     LDS_WAIT(); asm volatile("" ::: "memory");
;     const int c = lane & 7;
; #pragma unroll
;     for (int j = 0; j < 4; ++j) { const int n = (lane >> 3) + 8 * j; const LAS float* s = scr + (8 * c) * 33 + n;
;         v4u o; o.x = pk2(s[0 * 33], s[1 * 33]); o.y = pk2(s[2 * 33], s[3 * 33]); o.z = pk2(s[4 * 33], s[5 * 33]); o.w = pk2(s[6 * 33], s[7 * 33]);
;         *(GAS v4u*)(WT + (size_t)(drow0 + n) * ldk + k0 + 8 * c) = o; }
;     LDS_WAIT(); asm volatile("" ::: "memory");
; }
; __global__ void __launch_bounds__(NWAVES * 64, 2) fwd_kernel(Args args) {
;     ...
;             if (r < 4 * I_POOL) { const int g = r / I_POOL; transpose_item(KIN(7) + (size_t)g * 512 * 1024, 512, 1024, (bf16*)(ws + WS_WPOOL), 512, g * 1024, scr, r % I_POOL, lane); continue; } r -= 4 * I_POOL;
.LBB0_44:
	s_andn2_b64 vcc, exec, s[4:5]
	s_cbranch_vccnz .LBB0_46
	s_add_i32 s6, s38, 0xffff8800
	s_lshr_b32 s6, s6, 8
	s_load_dwordx2 s[4:5], s[0:1], 56
	s_waitcnt lgkmcnt(0)
	s_lshl_b64 s[8:9], s[6:7], 21
	s_add_u32 s4, s4, s8
	s_addc_u32 s5, s5, s9
	s_and_b32 s9, s11, 0x3e0
	s_lshl_b32 s6, s6, 10
	s_and_b32 s8, s17, 0x1c0
	s_lshl_b32 s14, s9, 2
	s_add_u32 s4, s4, s14
	v_or_b32_e32 v4, s8, v39
	s_addc_u32 s5, s5, 0
	s_waitcnt lgkmcnt(0)
	v_lshl_add_u64 v[2:3], s[4:5], 0, v[40:41]
	v_lshlrev_b32_e32 v4, 12, v4
	v_mov_b32_e32 v5, v41
	v_lshl_add_u64 v[30:31], v[2:3], 0, v[4:5]
	v_add_co_u32_e32 v10, vcc, s30, v30
	s_or_b32 s4, s6, s9
	s_nop 0
	v_addc_co_u32_e32 v11, vcc, 0, v31, vcc
	global_load_dwordx4 v[2:5], v[30:31], off nt
	global_load_dwordx4 v[6:9], v[10:11], off nt
	v_add_co_u32_e32 v10, vcc, s31, v30
	v_mov_b32_e32 v35, v41
	s_nop 0
	v_addc_co_u32_e32 v11, vcc, 0, v31, vcc
	v_add_co_u32_e32 v14, vcc, s33, v30
	s_lshl_b32 s6, s8, 1
	s_nop 0
	v_addc_co_u32_e32 v15, vcc, 0, v31, vcc
	v_add_co_u32_e32 v18, vcc, s19, v30
	global_load_dwordx4 v[10:13], v[10:11], off nt
	s_nop 0
	global_load_dwordx4 v[14:17], v[14:15], off nt
	v_addc_co_u32_e32 v19, vcc, 0, v31, vcc
	v_add_co_u32_e32 v22, vcc, s34, v30
	v_or_b32_e32 v34, s4, v39
	s_nop 0
	v_addc_co_u32_e32 v23, vcc, 0, v31, vcc
	global_load_dwordx4 v[18:21], v[18:19], off nt
	s_nop 0
	global_load_dwordx4 v[22:25], v[22:23], off nt
	v_add_co_u32_e32 v26, vcc, s35, v30
	v_lshl_add_u64 v[56:57], v[46:47], 0, s[6:7]
	s_nop 0
	v_addc_co_u32_e32 v27, vcc, 0, v31, vcc
	global_load_dwordx4 v[26:29], v[26:27], off nt
	v_add_co_u32_e32 v30, vcc, s36, v30
	v_lshlrev_b64 v[34:35], 10, v[34:35]
	s_nop 0
	v_addc_co_u32_e32 v31, vcc, 0, v31, vcc
	global_load_dwordx4 v[30:33], v[30:31], off nt
	v_lshl_add_u64 v[34:35], v[56:57], 0, v[34:35]
	v_mov_b32_e32 v37, v41
	v_or_b32_e32 v36, s4, v58
	v_lshlrev_b64 v[36:37], 10, v[36:37]
	v_lshl_add_u64 v[36:37], v[56:57], 0, v[36:37]
	s_waitcnt vmcnt(0)
	ds_write2_b32 v62, v2, v3 offset1:1
	ds_write2_b32 v62, v4, v5 offset0:2 offset1:3
	ds_write2_b32 v63, v6, v7 offset1:1
	ds_write2_b32 v64, v8, v9 offset1:1
	ds_write2_b32 v65, v10, v11 offset1:1
	ds_write2_b32 v66, v12, v13 offset1:1
	ds_write2_b32 v67, v14, v15 offset1:1
	ds_write2_b32 v68, v16, v17 offset1:1
	ds_write2_b32 v69, v18, v19 offset1:1
	ds_write2_b32 v70, v20, v21 offset1:1
	ds_write2_b32 v71, v22, v23 offset1:1
	ds_write2_b32 v72, v24, v25 offset1:1
	ds_write2_b32 v73, v26, v27 offset1:1
	ds_write2_b32 v74, v28, v29 offset1:1
	ds_write2_b32 v75, v30, v31 offset1:1
	ds_write2_b32 v76, v32, v33 offset1:1
	s_waitcnt lgkmcnt(0)
	ds_read2_b32 v[6:7], v61 offset0:33 offset1:41
	ds_read2_b32 v[8:9], v61 offset1:8
	ds_read2_b32 v[10:11], v61 offset0:66 offset1:74
	ds_read2_b32 v[12:13], v61 offset0:99 offset1:107
	ds_read2_b32 v[14:15], v61 offset0:132 offset1:140
	ds_read2_b32 v[16:17], v61 offset0:165 offset1:173
	ds_read2_b32 v[18:19], v61 offset0:198 offset1:206
	ds_read2_b32 v[20:21], v61 offset0:231 offset1:239
	ds_read2_b32 v[22:23], v61 offset0:49 offset1:57
	ds_read2_b32 v[24:25], v61 offset0:16 offset1:24
	ds_read2_b32 v[26:27], v61 offset0:82 offset1:90
	s_waitcnt lgkmcnt(0)
	v_cvt_pk_bf16_f32 v2, v8, v6
	v_cvt_pk_bf16_f32 v3, v10, v12
	v_cvt_pk_bf16_f32 v4, v14, v16
	v_cvt_pk_bf16_f32 v5, v18, v20
	global_store_dwordx4 v[34:35], v[2:5], off
	v_cvt_pk_bf16_f32 v6, v9, v7
	v_cvt_pk_bf16_f32 v7, v11, v13
	v_cvt_pk_bf16_f32 v8, v15, v17
	v_cvt_pk_bf16_f32 v9, v19, v21
	ds_read2_b32 v[10:11], v61 offset0:115 offset1:123
	ds_read2_b32 v[12:13], v61 offset0:148 offset1:156
	ds_read2_b32 v[14:15], v61 offset0:181 offset1:189
	ds_read2_b32 v[16:17], v61 offset0:214 offset1:222
	ds_read2_b32 v[18:19], v61 offset0:247 offset1:255
	global_store_dwordx4 v[36:37], v[6:9], off
	v_cvt_pk_bf16_f32 v2, v24, v22
	s_waitcnt lgkmcnt(4)
	v_cvt_pk_bf16_f32 v3, v26, v10
	v_or_b32_e32 v6, s4, v59
	v_mov_b32_e32 v7, v41
	v_lshlrev_b64 v[6:7], 10, v[6:7]
	s_waitcnt lgkmcnt(2)
	v_cvt_pk_bf16_f32 v4, v12, v14
	s_waitcnt lgkmcnt(0)
	v_cvt_pk_bf16_f32 v5, v16, v18
	v_lshl_add_u64 v[6:7], v[56:57], 0, v[6:7]
	global_store_dwordx4 v[6:7], v[2:5], off
	v_or_b32_e32 v6, s4, v60
	v_mov_b32_e32 v7, v41
	v_lshlrev_b64 v[6:7], 10, v[6:7]
	v_cvt_pk_bf16_f32 v2, v25, v23
	v_cvt_pk_bf16_f32 v3, v27, v11
	v_cvt_pk_bf16_f32 v4, v13, v15
	v_cvt_pk_bf16_f32 v5, v17, v19
	v_lshl_add_u64 v[6:7], v[56:57], 0, v[6:7]
	global_store_dwordx4 v[6:7], v[2:5], off
	s_waitcnt lgkmcnt(0)

; #define GAS __attribute__((address_space(1)))
; #define LAS __attribute__((address_space(3)))
; #define LDS_WAIT() asm volatile("s_waitcnt lgkmcnt(0)" ::: "memory")
; __device__ __forceinline__ unsigned pk4_fp8(float a, float b, float c, float d) { unsigned w = 0u; w = __builtin_amdgcn_cvt_pk_fp8_f32(a, b, w, false); w = __builtin_amdgcn_cvt_pk_fp8_f32(c, d, w, true); return w; }
; __device__ __forceinline__ void transpose_item_f8(const float* W, int K, int N, unsigned char* WT8, int ldk, LAS float* scr, int item, int lane) {
;     const int nblk = N / 32, kb = item / nblk, nb = item % nblk, k0 = 64 * kb, n0 = 32 * nb;
;     f32x4 wv[8]; const int kr = lane >> 3, nq = (lane & 7) * 4;
; #pragma unroll
;     for (int i = 0; i < 8; ++i) wv[i] = *(const GAS f32x4*)(W + (size_t)(k0 + 8 * i + kr) * N + n0 + nq);
; #pragma unroll
;     for (int i = 0; i < 8; ++i) { const int kk = 8 * i + kr; const f32x4 w = wv[i]; LAS float* d = scr + kk * 33 + nq; d[0] = w.x; d[1] = w.y; d[2] = w.z; d[3] = w.w; }
;     LDS_WAIT(); asm volatile("" ::: "memory");
;     const int c = lane & 7;
; #pragma unroll
;     for (int j = 0; j < 4; ++j) { const int n = (lane >> 3) + 8 * j; const LAS float* s = scr + (8 * c) * 33 + n;
;         v2u o; o.x = pk4_fp8(s[0 * 33] * W8SCALE, s[1 * 33] * W8SCALE, s[2 * 33] * W8SCALE, s[3 * 33] * W8SCALE); o.y = pk4_fp8(s[4 * 33] * W8SCALE, s[5 * 33] * W8SCALE, s[6 * 33] * W8SCALE, s[7 * 33] * W8SCALE);
;         *(GAS v2u*)(WT8 + (size_t)(n0 + n) * ldk + k0 + 8 * c) = o; }
;     LDS_WAIT(); asm volatile("" ::: "memory");
; }
; __global__ void __launch_bounds__(NWAVES * 64, 2) fwd_kernel(Args args) {
;     ...
;             if (r < I_ATT) { transpose_item_f8(KIN(6), NQ, DM, ws + WS_WATT, NQ, scr, r, lane); continue; } r -= I_ATT;
.LBB0_47:
	s_andn2_b64 vcc, exec, s[4:5]
	s_cbranch_vccnz .LBB0_49
	s_add_i32 s4, s38, 0xffff9800
	s_lshr_b32 s4, s4, 1
	s_and_b32 s6, s4, 0x7c0
	s_add_i32 s4, s11, 0xfff30000
	s_and_b32 s4, s4, 0xfe0
	s_load_dwordx2 s[8:9], s[0:1], 48
	s_waitcnt lgkmcnt(0)
	s_lshl_b32 s5, s4, 2
	s_add_u32 s8, s8, s5
	v_or_b32_e32 v4, s6, v39
	s_addc_u32 s9, s9, 0
	s_waitcnt lgkmcnt(0)
	v_lshl_add_u64 v[2:3], s[8:9], 0, v[40:41]
	v_lshlrev_b32_e32 v4, 14, v4
	v_mov_b32_e32 v5, v41
	v_lshl_add_u64 v[30:31], v[2:3], 0, v[4:5]
	v_add_co_u32_e32 v10, vcc, s19, v30
	v_mov_b32_e32 v34, v41
	s_nop 0
	v_addc_co_u32_e32 v11, vcc, 0, v31, vcc
	v_add_co_u32_e32 v18, vcc, s20, v30
	global_load_dwordx4 v[2:5], v[30:31], off nt
	global_load_dwordx4 v[6:9], v[10:11], off nt
	v_addc_co_u32_e32 v19, vcc, 0, v31, vcc
	v_add_co_u32_e32 v20, vcc, s21, v30
	v_mov_b32_e32 v35, v41
	s_nop 0
	v_addc_co_u32_e32 v21, vcc, 0, v31, vcc
	v_add_co_u32_e32 v26, vcc, s22, v30
	global_load_dwordx4 v[10:13], v[18:19], off nt
	global_load_dwordx4 v[14:17], v[20:21], off nt
	v_addc_co_u32_e32 v27, vcc, 0, v31, vcc
	v_add_co_u32_e32 v28, vcc, s23, v30
	v_mov_b32_e32 v56, v41
	s_nop 0
	v_addc_co_u32_e32 v29, vcc, 0, v31, vcc
	global_load_dwordx4 v[18:21], v[26:27], off nt
	global_load_dwordx4 v[22:25], v[28:29], off nt
	v_add_co_u32_e32 v26, vcc, s24, v30
	v_mov_b32_e32 v57, v41
	s_nop 0
	v_addc_co_u32_e32 v27, vcc, 0, v31, vcc
	global_load_dwordx4 v[26:29], v[26:27], off nt
	v_add_co_u32_e32 v30, vcc, s25, v30
	v_or_b32_e32 v36, s4, v39
	s_nop 0
	v_addc_co_u32_e32 v31, vcc, 0, v31, vcc
	global_load_dwordx4 v[30:33], v[30:31], off nt
	v_mov_b32_e32 v37, v41
	v_lshl_add_u64 v[78:79], v[48:49], 0, s[6:7]
	v_lshlrev_b32_e32 v36, 11, v36
	v_lshl_add_u64 v[36:37], v[78:79], 0, v[36:37]
	s_waitcnt vmcnt(0)
	ds_write2_b32 v62, v2, v3 offset1:1
	ds_write2_b32 v62, v4, v5 offset0:2 offset1:3
	ds_write2_b32 v63, v6, v7 offset1:1
	ds_write2_b32 v64, v8, v9 offset1:1
	ds_write2_b32 v65, v10, v11 offset1:1
	ds_write2_b32 v66, v12, v13 offset1:1
	ds_write2_b32 v67, v14, v15 offset1:1
	ds_write2_b32 v68, v16, v17 offset1:1
	ds_write2_b32 v69, v18, v19 offset1:1
	ds_write2_b32 v70, v20, v21 offset1:1
	ds_write2_b32 v71, v22, v23 offset1:1
	ds_write2_b32 v72, v24, v25 offset1:1
	ds_write2_b32 v73, v26, v27 offset1:1
	ds_write2_b32 v74, v28, v29 offset1:1
	ds_write2_b32 v75, v30, v31 offset1:1
	ds_write2_b32 v76, v32, v33 offset1:1
	s_waitcnt lgkmcnt(0)
	ds_read2_b32 v[2:3], v61 offset1:8
	ds_read2_b32 v[4:5], v61 offset0:33 offset1:41
	ds_read2_b32 v[6:7], v61 offset0:66 offset1:74
	ds_read2_b32 v[8:9], v61 offset0:99 offset1:107
	ds_read2_b32 v[10:11], v61 offset0:132 offset1:140
	ds_read2_b32 v[12:13], v61 offset0:165 offset1:173
	ds_read2_b32 v[14:15], v61 offset0:198 offset1:206
	ds_read2_b32 v[16:17], v61 offset0:231 offset1:239
	s_waitcnt lgkmcnt(0)
	v_mul_f32_e32 v2, 0x42800000, v2
	v_mul_f32_e32 v4, 0x42800000, v4
	v_mul_f32_e32 v10, 0x42800000, v10
	v_mul_f32_e32 v12, 0x42800000, v12
	v_mul_f32_e32 v3, 0x42800000, v3
	v_mul_f32_e32 v5, 0x42800000, v5
	v_cvt_pk_fp8_f32 v34, v2, v4
	v_cvt_pk_fp8_f32 v35, v10, v12
	v_mul_f32_e32 v2, 0x42800000, v11
	v_cvt_pk_fp8_f32 v56, v3, v5
	v_mul_f32_e32 v3, 0x42800000, v13
	v_cvt_pk_fp8_f32 v57, v2, v3
	v_mul_f32_e32 v6, 0x42800000, v6
	v_mul_f32_e32 v8, 0x42800000, v8
	v_mul_f32_e32 v14, 0x42800000, v14
	v_mul_f32_e32 v16, 0x42800000, v16
	v_mul_f32_e32 v7, 0x42800000, v7
	v_mul_f32_e32 v9, 0x42800000, v9
	v_cvt_pk_fp8_f32 v34, v6, v8 op_sel:[0,0,1]
	v_cvt_pk_fp8_f32 v35, v14, v16 op_sel:[0,0,1]
	v_mul_f32_e32 v2, 0x42800000, v15
	v_mul_f32_e32 v3, 0x42800000, v17
	v_cvt_pk_fp8_f32 v56, v7, v9 op_sel:[0,0,1]
	v_cvt_pk_fp8_f32 v57, v2, v3 op_sel:[0,0,1]
	v_or_b32_e32 v2, s4, v58
	v_lshlrev_b32_e32 v2, 11, v2
	v_mov_b32_e32 v3, v41
	global_store_dwordx2 v[36:37], v[34:35], off
	v_lshl_add_u64 v[2:3], v[78:79], 0, v[2:3]
	ds_read2_b32 v[4:5], v61 offset0:16 offset1:24
	ds_read2_b32 v[6:7], v61 offset0:49 offset1:57
	ds_read2_b32 v[8:9], v61 offset0:82 offset1:90
	global_store_dwordx2 v[2:3], v[56:57], off
	ds_read2_b32 v[2:3], v61 offset0:115 offset1:123
	ds_read2_b32 v[10:11], v61 offset0:148 offset1:156
	ds_read2_b32 v[12:13], v61 offset0:181 offset1:189
	s_waitcnt lgkmcnt(5)
	v_mul_f32_e32 v4, 0x42800000, v4
	s_waitcnt lgkmcnt(4)
	v_mul_f32_e32 v6, 0x42800000, v6
	v_mov_b32_e32 v14, v41
	ds_read2_b32 v[16:17], v61 offset0:214 offset1:222
	ds_read2_b32 v[18:19], v61 offset0:247 offset1:255
	v_cvt_pk_fp8_f32 v14, v4, v6
	s_waitcnt lgkmcnt(3)
	v_mul_f32_e32 v4, 0x42800000, v10
	s_waitcnt lgkmcnt(2)
	v_mul_f32_e32 v6, 0x42800000, v12
	v_mov_b32_e32 v15, v41
	v_cvt_pk_fp8_f32 v15, v4, v6
	v_mul_f32_e32 v8, 0x42800000, v8
	v_mul_f32_e32 v2, 0x42800000, v2
	v_cvt_pk_fp8_f32 v14, v8, v2 op_sel:[0,0,1]
	s_waitcnt lgkmcnt(1)
	v_mul_f32_e32 v2, 0x42800000, v16
	s_waitcnt lgkmcnt(0)
	v_mul_f32_e32 v4, 0x42800000, v18
	v_cvt_pk_fp8_f32 v15, v2, v4 op_sel:[0,0,1]
	v_or_b32_e32 v2, s4, v59
	v_lshlrev_b32_e32 v20, 11, v2
	v_mul_f32_e32 v4, 0x42800000, v5
	v_mul_f32_e32 v5, 0x42800000, v7
	v_mov_b32_e32 v2, v41
	v_mul_f32_e32 v7, 0x42800000, v3
	v_cvt_pk_fp8_f32 v2, v4, v5
	v_mul_f32_e32 v4, 0x42800000, v11
	v_mul_f32_e32 v5, 0x42800000, v13
	v_mov_b32_e32 v3, v41
	v_cvt_pk_fp8_f32 v3, v4, v5
	v_mul_f32_e32 v6, 0x42800000, v9
	v_mul_f32_e32 v4, 0x42800000, v17
	v_mul_f32_e32 v5, 0x42800000, v19
	v_cvt_pk_fp8_f32 v2, v6, v7 op_sel:[0,0,1]
	v_cvt_pk_fp8_f32 v3, v4, v5 op_sel:[0,0,1]
	v_or_b32_e32 v4, s4, v60
	v_mov_b32_e32 v21, v41
	v_lshlrev_b32_e32 v4, 11, v4
	v_mov_b32_e32 v5, v41
	v_lshl_add_u64 v[20:21], v[78:79], 0, v[20:21]
	v_lshl_add_u64 v[4:5], v[78:79], 0, v[4:5]
	global_store_dwordx2 v[20:21], v[14:15], off
	global_store_dwordx2 v[4:5], v[2:3], off
	s_waitcnt lgkmcnt(0)

; #define GAS __attribute__((address_space(1)))
; #define LAS __attribute__((address_space(3)))
; #define LDS_WAIT() asm volatile("s_waitcnt lgkmcnt(0)" ::: "memory")
; __device__ __forceinline__ unsigned pk2(float lo, float hi) { return pg8::cvt_pk_bf16(lo, hi); }
; __device__ __forceinline__ unsigned pk4_fp8(float a, float b, float c, float d) { unsigned w = 0u; w = __builtin_amdgcn_cvt_pk_fp8_f32(a, b, w, false); w = __builtin_amdgcn_cvt_pk_fp8_f32(c, d, w, true); return w; }
; __device__ __forceinline__ void transpose_item_in(const float* W, bf16* WTu, unsigned char* WT8, LAS float* scr, int item, int lane) {
;     constexpr int K = DM, N = INW;
;     const int nblk = N / 32, kb = item / nblk, nb = item % nblk, k0 = 64 * kb, n0 = 32 * nb;
;     f32x4 wv[8]; const int kr = lane >> 3, nq = (lane & 7) * 4;
; #pragma unroll
;     for (int i = 0; i < 8; ++i) wv[i] = *(const GAS f32x4*)(W + (size_t)(k0 + 8 * i + kr) * N + n0 + nq);
; #pragma unroll
;     for (int i = 0; i < 8; ++i) { const int kk = 8 * i + kr; const f32x4 w = wv[i]; LAS float* d = scr + kk * 33 + nq; d[0] = w.x; d[1] = w.y; d[2] = w.z; d[3] = w.w; }
;     LDS_WAIT(); asm volatile("" ::: "memory");
;     const int c = lane & 7;
;     if (n0 >= 3072 && n0 < 5120) {
; #pragma unroll
;         for (int j = 0; j < 4; ++j) { const int n = (lane >> 3) + 8 * j; const LAS float* s = scr + (8 * c) * 33 + n;
;             v4u o; o.x = pk2(s[0 * 33], s[1 * 33]); o.y = pk2(s[2 * 33], s[3 * 33]); o.z = pk2(s[4 * 33], s[5 * 33]); o.w = pk2(s[6 * 33], s[7 * 33]);
;             *(GAS v4u*)(WTu + (size_t)(n0 - 3072 + n) * K + k0 + 8 * c) = o; }
;     } else {
;         const int r0 = n0 < 3072 ? n0 : n0 - 2048;
; #pragma unroll
;         for (int j = 0; j < 4; ++j) { const int n = (lane >> 3) + 8 * j; const LAS float* s = scr + (8 * c) * 33 + n;
;             v2u o; o.x = pk4_fp8(s[0 * 33] * W8SCALE, s[1 * 33] * W8SCALE, s[2 * 33] * W8SCALE, s[3 * 33] * W8SCALE); o.y = pk4_fp8(s[4 * 33] * W8SCALE, s[5 * 33] * W8SCALE, s[6 * 33] * W8SCALE, s[7 * 33] * W8SCALE);
;             *(GAS v2u*)(WT8 + (size_t)(r0 + n) * K + k0 + 8 * c) = o; }
;     }
;     LDS_WAIT(); asm volatile("" ::: "memory");
; }
; __global__ void __launch_bounds__(NWAVES * 64, 2) fwd_kernel(Args args) {
;     ...
;             if (r < I_IN) { transpose_item_in(KIN(3), (bf16*)(ws + WS_WIN), ws + WS_WIN8, scr, r, lane); continue; } r -= I_IN;
.LBB0_50:
	s_andn2_b64 vcc, exec, s[4:5]
	s_cbranch_vccnz .LBB0_15
	s_mul_hi_i32 s4, s38, 0x4ec4ec4f
	s_lshr_b32 s5, s4, 31
	s_ashr_i32 s4, s4, 7
	s_add_i32 s4, s4, s5
	s_mul_i32 s5, s4, 0xfffffe60
	s_lshl_b32 s8, s4, 6
	s_mulk_i32 s4, 0xcc00
	s_add_i32 s4, s11, s4
	s_add_i32 s6, s38, s5
	s_ashr_i32 s5, s4, 31
	s_load_dwordx2 s[14:15], s[0:1], 24
	s_waitcnt lgkmcnt(0)
	s_lshl_b64 s[40:41], s[4:5], 2
	s_add_u32 s14, s14, s40
	s_addc_u32 s15, s15, s41
	v_or_b32_e32 v32, s8, v39
	v_lshl_add_u64 v[30:31], s[14:15], 0, v[40:41]
	v_mad_i64_i32 v[10:11], s[14:15], v32, s37, v[30:31]
	s_waitcnt lgkmcnt(0)
	v_or_b32_e32 v2, 8, v32
	v_mad_i64_i32 v[12:13], s[14:15], v2, s37, v[30:31]
	global_load_dwordx4 v[2:5], v[10:11], off nt
	global_load_dwordx4 v[6:9], v[12:13], off nt
	v_or_b32_e32 v10, 16, v32
	v_mad_i64_i32 v[18:19], s[14:15], v10, s37, v[30:31]
	v_or_b32_e32 v10, 24, v32
	v_mad_i64_i32 v[20:21], s[14:15], v10, s37, v[30:31]
	global_load_dwordx4 v[10:13], v[18:19], off nt
	global_load_dwordx4 v[14:17], v[20:21], off nt
	v_or_b32_e32 v18, 32, v32
	v_mad_i64_i32 v[26:27], s[14:15], v18, s37, v[30:31]
	v_or_b32_e32 v18, 40, v32
	v_mad_i64_i32 v[28:29], s[14:15], v18, s37, v[30:31]
	global_load_dwordx4 v[18:21], v[26:27], off nt
	global_load_dwordx4 v[22:25], v[28:29], off nt
	v_or_b32_e32 v26, 48, v32
	v_mad_i64_i32 v[26:27], s[14:15], v26, s37, v[30:31]
	global_load_dwordx4 v[26:29], v[26:27], off nt
	v_or_b32_e32 v32, 56, v32
	v_mad_i64_i32 v[30:31], s[14:15], v32, s37, v[30:31]
	global_load_dwordx4 v[30:33], v[30:31], off nt
	s_add_i32 s5, s6, 0xffffffa0
	s_cmp_gt_u32 s5, 63
	s_mov_b64 s[14:15], -1
	s_waitcnt vmcnt(0)
	ds_write2_b32 v62, v2, v3 offset1:1
	ds_write2_b32 v62, v4, v5 offset0:2 offset1:3
	ds_write2_b32 v63, v6, v7 offset1:1
	ds_write2_b32 v64, v8, v9 offset1:1
	ds_write2_b32 v65, v10, v11 offset1:1
	ds_write2_b32 v66, v12, v13 offset1:1
	ds_write2_b32 v67, v14, v15 offset1:1
	ds_write2_b32 v68, v16, v17 offset1:1
	ds_write2_b32 v69, v18, v19 offset1:1
	ds_write2_b32 v70, v20, v21 offset1:1
	ds_write2_b32 v71, v22, v23 offset1:1
	ds_write2_b32 v72, v24, v25 offset1:1
	ds_write2_b32 v73, v26, v27 offset1:1
	ds_write2_b32 v74, v28, v29 offset1:1
	ds_write2_b32 v75, v30, v31 offset1:1
	ds_write2_b32 v76, v32, v33 offset1:1
	s_waitcnt lgkmcnt(0)
	ds_read2_b32 v[2:3], v61 offset0:99 offset1:165
	s_cbranch_scc0 .LBB0_53
	ds_read2_b32 v[4:5], v61 offset1:8
	ds_read2_b32 v[6:7], v61 offset0:33 offset1:41
	ds_read2_b32 v[12:13], v61 offset0:123 offset1:132
	ds_read2_b32 v[8:9], v61 offset0:66 offset1:74
	v_mov_b32_e32 v14, v41
	s_waitcnt lgkmcnt(0)
	v_mul_f32_e32 v4, 0x42800000, v4
	v_mul_f32_e32 v6, 0x42800000, v6
	ds_read2_b32 v[16:17], v61 offset0:198 offset1:206
	ds_read2_b32 v[18:19], v61 offset0:231 offset1:239
	v_cvt_pk_fp8_f32 v14, v4, v6
	v_mul_f32_e32 v4, 0x42800000, v13
	v_mul_f32_e32 v6, 0x42800000, v3
	v_mov_b32_e32 v15, v41
	v_cvt_pk_fp8_f32 v15, v4, v6
	s_add_i32 s5, s4, 0xfffff800
	s_cmpk_lt_i32 s6, 0x60
	s_cselect_b32 s5, s4, s5
	v_mul_f32_e32 v8, 0x42800000, v8
	v_mul_f32_e32 v20, 0x42800000, v2
	s_waitcnt lgkmcnt(1)
	v_mul_f32_e32 v4, 0x42800000, v16
	s_waitcnt lgkmcnt(0)
	v_mul_f32_e32 v6, 0x42800000, v18
	v_cvt_pk_fp8_f32 v14, v8, v20 op_sel:[0,0,1]
	v_cvt_pk_fp8_f32 v15, v4, v6 op_sel:[0,0,1]
	v_or_b32_e32 v20, s5, v39
	s_ashr_i32 s9, s8, 31
	v_ashrrev_i32_e32 v21, 31, v20
	v_lshl_add_u64 v[10:11], v[50:51], 0, s[8:9]
	v_lshlrev_b64 v[20:21], 12, v[20:21]
	v_lshl_add_u64 v[20:21], v[10:11], 0, v[20:21]
	global_store_dwordx2 v[20:21], v[14:15], off
	v_mul_f32_e32 v13, 0x42800000, v5
	ds_read2_b32 v[4:5], v61 offset0:107 offset1:115
	v_mul_f32_e32 v15, 0x42800000, v7
	v_mul_f32_e32 v16, 0x42800000, v9
	ds_read2_b32 v[6:7], v61 offset0:140 offset1:148
	ds_read2_b32 v[8:9], v61 offset0:156 offset1:173
	v_mov_b32_e32 v14, v41
	v_cvt_pk_fp8_f32 v14, v13, v15
	v_mov_b32_e32 v15, v41
	s_waitcnt lgkmcnt(1)
	v_mul_f32_e32 v6, 0x42800000, v6
	s_waitcnt lgkmcnt(0)
	v_mul_f32_e32 v9, 0x42800000, v9
	v_cvt_pk_fp8_f32 v15, v6, v9
	v_mul_f32_e32 v4, 0x42800000, v4
	v_cvt_pk_fp8_f32 v14, v16, v4 op_sel:[0,0,1]
	v_mul_f32_e32 v4, 0x42800000, v17
	v_mul_f32_e32 v6, 0x42800000, v19
	v_cvt_pk_fp8_f32 v15, v4, v6 op_sel:[0,0,1]
	v_or_b32_e32 v16, s5, v58
	v_ashrrev_i32_e32 v17, 31, v16
	v_lshlrev_b64 v[16:17], 12, v[16:17]
	ds_read2_b32 v[18:19], v61 offset0:16 offset1:24
	ds_read2_b32 v[20:21], v61 offset0:49 offset1:57
	ds_read2_b32 v[22:23], v61 offset0:82 offset1:90
	v_lshl_add_u64 v[16:17], v[10:11], 0, v[16:17]
	global_store_dwordx2 v[16:17], v[14:15], off
	ds_read2_b32 v[14:15], v61 offset0:181 offset1:189
	s_waitcnt lgkmcnt(3)
	v_mul_f32_e32 v6, 0x42800000, v18
	s_waitcnt lgkmcnt(2)
	v_mul_f32_e32 v9, 0x42800000, v20
	v_mov_b32_e32 v4, v41
	v_cvt_pk_fp8_f32 v4, v6, v9
	v_mul_f32_e32 v9, 0x42800000, v7
	ds_read2_b32 v[6:7], v61 offset0:214 offset1:222
	ds_read2_b32 v[16:17], v61 offset0:247 offset1:255
	v_mul_f32_e32 v18, 0x42800000, v5
	s_waitcnt lgkmcnt(2)
	v_mul_f32_e32 v14, 0x42800000, v14
	v_mov_b32_e32 v5, v41
	v_cvt_pk_fp8_f32 v5, v9, v14
	v_mul_f32_e32 v13, 0x42800000, v22
	s_waitcnt lgkmcnt(1)
	v_mul_f32_e32 v6, 0x42800000, v6
	s_waitcnt lgkmcnt(0)
	v_mul_f32_e32 v9, 0x42800000, v16
	v_cvt_pk_fp8_f32 v4, v13, v18 op_sel:[0,0,1]
	v_cvt_pk_fp8_f32 v5, v6, v9 op_sel:[0,0,1]
	v_or_b32_e32 v24, s5, v59
	v_ashrrev_i32_e32 v25, 31, v24
	v_lshlrev_b64 v[24:25], 12, v[24:25]
	v_lshl_add_u64 v[24:25], v[10:11], 0, v[24:25]
	global_store_dwordx2 v[24:25], v[4:5], off
	v_mul_f32_e32 v5, 0x42800000, v19
	v_mul_f32_e32 v6, 0x42800000, v21
	v_mov_b32_e32 v4, v41
	v_cvt_pk_fp8_f32 v4, v5, v6
	v_mul_f32_e32 v6, 0x42800000, v8
	v_mul_f32_e32 v8, 0x42800000, v15
	v_mov_b32_e32 v5, v41
	v_cvt_pk_fp8_f32 v5, v6, v8
	v_mul_f32_e32 v9, 0x42800000, v23
	v_mul_f32_e32 v12, 0x42800000, v12
	v_mul_f32_e32 v6, 0x42800000, v7
	v_mul_f32_e32 v7, 0x42800000, v17
	v_cvt_pk_fp8_f32 v4, v9, v12 op_sel:[0,0,1]
	v_cvt_pk_fp8_f32 v5, v6, v7 op_sel:[0,0,1]
	v_or_b32_e32 v6, s5, v60
	v_ashrrev_i32_e32 v7, 31, v6
	v_lshlrev_b64 v[6:7], 12, v[6:7]
	v_lshl_add_u64 v[6:7], v[10:11], 0, v[6:7]
	global_store_dwordx2 v[6:7], v[4:5], off
	s_mov_b64 s[14:15], 0

; #define GAS __attribute__((address_space(1)))
; __device__ __forceinline__ void rms_row_to_bf16(const float* xrow, const float* g, bf16* orow, int lane, unsigned char* o8row = nullptr) {
;     const GAS f32x4* xr = (const GAS f32x4*)xrow + lane;
;     f32x4 v[16]; float s = 0.f;
; #pragma unroll
;     for (int j = 0; j < 16; ++j) { v[j] = xr[64 * j]; s += (v[j].x * v[j].x + v[j].y * v[j].y) + (v[j].z * v[j].z + v[j].w * v[j].w); }
;     const float inv = 1.0f / sqrtf(wave_sum(s) * (1.f / DM) + EPS);
.LBB0_72:
	s_load_dwordx2 s[20:21], s[0:1], 0x80
	s_waitcnt lgkmcnt(0)
	global_load_dwordx4 v[62:65], v66, s[22:23] nt
	global_load_dwordx4 v[58:61], v66, s[22:23] offset:1024 nt
	global_load_dwordx4 v[42:45], v66, s[22:23] offset:3072 nt
	v_lshl_add_u64 v[2:3], s[22:23], 0, v[66:67]
	global_load_dwordx4 v[54:57], v66, s[22:23] offset:2048 nt
	v_add_co_u32_e32 v110, vcc, s25, v2
	s_lshl_b64 s[30:31], s[4:5], 12
	s_nop 0
	v_addc_co_u32_e32 v111, vcc, 0, v3, vcc
	global_load_dwordx4 v[50:53], v[110:111], off offset:-4096 nt
	v_add_co_u32_e32 v4, vcc, s24, v2
	s_lshl_b64 s[22:23], s[4:5], 13
	s_nop 0
	v_addc_co_u32_e32 v5, vcc, 0, v3, vcc
	global_load_dwordx4 v[34:37], v[4:5], off offset:2048 nt
	global_load_dwordx4 v[46:49], v[4:5], off offset:1024 nt
	global_load_dwordx4 v[38:41], v[4:5], off offset:3072 nt
	global_load_dwordx4 v[22:25], v[110:111], off offset:1024 nt
	global_load_dwordx4 v[30:33], v[110:111], off nt
	global_load_dwordx4 v[26:29], v[110:111], off offset:2048 nt
	v_add_co_u32_e32 v112, vcc, s26, v2
	s_add_u32 s22, s18, s22
	s_nop 0
	v_addc_co_u32_e32 v113, vcc, 0, v3, vcc
	global_load_dwordx4 v[18:21], v[110:111], off offset:3072 nt
	global_load_dwordx4 v[10:13], v[112:113], off nt
	global_load_dwordx4 v[14:17], v[112:113], off offset:1024 nt
	global_load_dwordx4 v[6:9], v[112:113], off offset:2048 nt
	global_load_dwordx4 v[2:5], v[112:113], off offset:3072 nt
	v_cmp_lt_i32_e32 vcc, v101, v100
	s_addc_u32 s23, s19, s23
	s_waitcnt vmcnt(0)
	v_pk_mul_f32 v[110:111], v[64:65], v[64:65]
	v_pk_mul_f32 v[112:113], v[62:63], v[62:63]
	v_pk_mul_f32 v[114:115], v[60:61], v[60:61]
	v_pk_mul_f32 v[116:117], v[58:59], v[58:59]
	v_pk_mov_b32 v[120:121], v[112:113], v[110:111] op_sel:[1,0]
	v_mov_b32_e32 v113, v111
	v_pk_mov_b32 v[110:111], v[116:117], v[114:115] op_sel:[1,0]
	v_mov_b32_e32 v117, v115
	v_mul_f32_e32 v98, v55, v55
	v_mul_f32_e32 v118, v57, v57
	v_pk_add_f32 v[112:113], v[120:121], v[112:113]
	v_pk_add_f32 v[110:111], v[110:111], v[116:117]
	v_mul_f32_e32 v109, v42, v42
	v_mul_f32_e32 v133, v43, v43
	v_mul_f32_e32 v127, v44, v44
	v_mul_f32_e32 v134, v45, v45
	v_pk_fma_f32 v[114:115], v[54:55], v[54:55], v[98:99] op_sel_hi:[1,1,0]
	v_pk_fma_f32 v[118:119], v[56:57], v[56:57], v[118:119] op_sel_hi:[1,1,0]
	v_pk_add_f32 v[112:113], v[112:113], v[112:113] op_sel:[0,1] op_sel_hi:[1,0]
	v_pk_add_f32 v[110:111], v[110:111], v[110:111] op_sel:[0,1] op_sel_hi:[1,0]
	v_pk_mul_f32 v[122:123], v[52:53], v[52:53]
	v_pk_mul_f32 v[124:125], v[50:51], v[50:51]
	v_mov_b32_e32 v115, v127
	v_mov_b32_e32 v119, v134
	v_mov_b32_e32 v113, v109
	v_mov_b32_e32 v111, v133
	v_pk_mov_b32 v[116:117], v[124:125], v[122:123] op_sel:[1,0]
	v_mov_b32_e32 v125, v123
	v_pk_add_f32 v[114:115], v[114:115], v[118:119]
	v_pk_add_f32 v[110:111], v[112:113], v[110:111]
	v_mul_f32_e32 v98, v47, v47
	v_mul_f32_e32 v126, v49, v49
	v_pk_add_f32 v[116:117], v[116:117], v[124:125]
	v_pk_add_f32 v[110:111], v[110:111], v[114:115]
	v_mul_f32_e32 v135, v34, v34
	v_mul_f32_e32 v136, v35, v35
	v_mul_f32_e32 v137, v36, v36
	v_mul_f32_e32 v138, v37, v37
	v_pk_fma_f32 v[120:121], v[46:47], v[46:47], v[98:99] op_sel_hi:[1,1,0]
	v_pk_fma_f32 v[122:123], v[48:49], v[48:49], v[126:127] op_sel_hi:[1,1,0]
	v_pk_add_f32 v[116:117], v[116:117], v[116:117] op_sel:[0,1] op_sel_hi:[1,0]
	v_pk_add_f32 v[110:111], v[110:111], v[110:111] op_sel:[0,1] op_sel_hi:[1,0]
	v_pk_mul_f32 v[128:129], v[40:41], v[40:41]
	v_pk_mul_f32 v[130:131], v[38:39], v[38:39]
	v_mov_b32_e32 v121, v137
	v_mov_b32_e32 v123, v138
	v_mov_b32_e32 v117, v136
	v_mov_b32_e32 v111, v135
	v_pk_mov_b32 v[126:127], v[130:131], v[128:129] op_sel:[1,0]
	v_mov_b32_e32 v131, v129
	v_pk_add_f32 v[120:121], v[120:121], v[122:123]
	v_pk_add_f32 v[110:111], v[110:111], v[116:117]
	v_mul_f32_e32 v132, v31, v31
	v_pk_add_f32 v[118:119], v[126:127], v[130:131]
	v_pk_add_f32 v[110:111], v[110:111], v[120:121]
	v_mul_f32_e32 v98, v33, v33
	v_mul_f32_e32 v139, v22, v22
	v_mul_f32_e32 v140, v23, v23
	v_mul_f32_e32 v141, v24, v24
	v_mul_f32_e32 v142, v25, v25
	v_pk_fma_f32 v[128:129], v[30:31], v[30:31], v[132:133] op_sel_hi:[1,1,0]
	v_pk_add_f32 v[118:119], v[118:119], v[118:119] op_sel:[0,1] op_sel_hi:[1,0]
	v_pk_add_f32 v[110:111], v[110:111], v[110:111] op_sel:[0,1] op_sel_hi:[1,0]
	v_pk_fma_f32 v[112:113], v[32:33], v[32:33], v[98:99] op_sel_hi:[1,1,0]
	v_mov_b32_e32 v119, v140
	v_mov_b32_e32 v111, v139
	v_mov_b32_e32 v129, v141
	v_mov_b32_e32 v113, v142
	v_pk_add_f32 v[110:111], v[110:111], v[118:119]
	v_pk_add_f32 v[112:113], v[128:129], v[112:113]
	v_pk_mul_f32 v[114:115], v[26:27], v[26:27]
	v_pk_add_f32 v[110:111], v[110:111], v[112:113]
	v_pk_mul_f32 v[112:113], v[28:29], v[28:29]
	v_mul_f32_e32 v98, v10, v10
	v_pk_mov_b32 v[116:117], v[114:115], v[112:113] op_sel:[1,0]
	v_mov_b32_e32 v115, v113
	v_pk_add_f32 v[112:113], v[116:117], v[114:115]
	v_mul_f32_e32 v109, v11, v11
	v_pk_add_f32 v[110:111], v[110:111], v[110:111] op_sel:[0,1] op_sel_hi:[1,0]
	v_pk_add_f32 v[112:113], v[112:113], v[112:113] op_sel:[0,1] op_sel_hi:[1,0]
	v_mov_b32_e32 v111, v98
	v_mov_b32_e32 v113, v109
	v_mul_f32_e32 v98, v19, v19
	v_mul_f32_e32 v114, v12, v12
	v_pk_add_f32 v[110:111], v[110:111], v[112:113]
	v_pk_fma_f32 v[112:113], v[18:19], v[18:19], v[98:99] op_sel_hi:[1,1,0]
	v_mul_f32_e32 v98, v21, v21
	v_mul_f32_e32 v116, v13, v13
	v_mov_b32_e32 v113, v114
	v_pk_fma_f32 v[114:115], v[20:21], v[20:21], v[98:99] op_sel_hi:[1,1,0]
	v_mul_f32_e32 v98, v2, v2
	v_mov_b32_e32 v115, v116
	v_pk_add_f32 v[112:113], v[112:113], v[114:115]
	v_pk_mul_f32 v[114:115], v[14:15], v[14:15]
	v_pk_add_f32 v[110:111], v[110:111], v[112:113]
	v_pk_mul_f32 v[112:113], v[16:17], v[16:17]
	v_mul_f32_e32 v109, v3, v3
	v_pk_mov_b32 v[116:117], v[114:115], v[112:113] op_sel:[1,0]
	v_mov_b32_e32 v115, v113
	v_pk_add_f32 v[112:113], v[116:117], v[114:115]
	v_pk_add_f32 v[110:111], v[110:111], v[110:111] op_sel:[0,1] op_sel_hi:[1,0]
	v_pk_add_f32 v[112:113], v[112:113], v[112:113] op_sel:[0,1] op_sel_hi:[1,0]
	v_mov_b32_e32 v111, v98
	v_mov_b32_e32 v113, v109
	v_mul_f32_e32 v98, v7, v7
	v_mul_f32_e32 v114, v4, v4
	v_pk_add_f32 v[110:111], v[110:111], v[112:113]
	v_pk_fma_f32 v[112:113], v[6:7], v[6:7], v[98:99] op_sel_hi:[1,1,0]
	v_mul_f32_e32 v98, v9, v9
	v_mul_f32_e32 v116, v5, v5
	v_mov_b32_e32 v113, v114
	v_pk_fma_f32 v[114:115], v[8:9], v[8:9], v[98:99] op_sel_hi:[1,1,0]
	v_cndmask_b32_e32 v109, v99, v101, vcc
	v_mov_b32_e32 v115, v116
	v_pk_add_f32 v[112:113], v[112:113], v[114:115]
	v_lshlrev_b32_e32 v109, 2, v109
	v_pk_add_f32 v[110:111], v[110:111], v[112:113]
	v_cmp_lt_i32_e32 vcc, v102, v100
	v_add_f32_e32 v98, v110, v111
	global_load_dwordx4 v[110:113], v[68:69], off
	ds_bpermute_b32 v109, v109, v98
	s_waitcnt lgkmcnt(0)
; #define GAS __attribute__((address_space(1)))
; __device__ __forceinline__ unsigned pk2(float lo, float hi) { return pg8::cvt_pk_bf16(lo, hi); }
; __device__ __forceinline__ unsigned pk4_fp8(float a, float b, float c, float d) { unsigned w = 0u; w = __builtin_amdgcn_cvt_pk_fp8_f32(a, b, w, false); w = __builtin_amdgcn_cvt_pk_fp8_f32(c, d, w, true); return w; }
; __device__ __forceinline__ void rms_row_to_bf16(const float* xrow, const float* g, bf16* orow, int lane, unsigned char* o8row = nullptr) {
;     ...
;     const float inv = 1.0f / sqrtf(wave_sum(s) * (1.f / DM) + EPS);
;     const GAS f32x4* gr = (const GAS f32x4*)g + lane;
;     GAS v2u* o8 = (GAS v2u*)orow + lane;
; #pragma unroll
;     for (int j = 0; j < 16; ++j) { const f32x4 gg = gr[64 * j]; const float a = v[j].x * inv * gg.x, b = v[j].y * inv * gg.y, c = v[j].z * inv * gg.z, d = v[j].w * inv * gg.w;
;         v2u w; w.x = pk2(a, b); w.y = pk2(c, d); o8[64 * j] = w;
;         if (o8row) ((GAS unsigned*)o8row)[lane + 64 * j] = pk4_fp8(a, b, c, d); }
	v_add_f32_e32 v98, v98, v109
	v_cndmask_b32_e32 v109, v99, v102, vcc
	v_lshlrev_b32_e32 v109, 2, v109
	ds_bpermute_b32 v109, v109, v98
	v_cmp_lt_i32_e32 vcc, v103, v100
	s_waitcnt lgkmcnt(0)
	v_add_f32_e32 v98, v98, v109
	v_cndmask_b32_e32 v109, v99, v103, vcc
	v_lshlrev_b32_e32 v109, 2, v109
	ds_bpermute_b32 v109, v109, v98
	v_cmp_lt_i32_e32 vcc, v104, v100
	s_waitcnt lgkmcnt(0)
	v_add_f32_e32 v98, v98, v109
	v_cndmask_b32_e32 v109, v99, v104, vcc
	v_lshlrev_b32_e32 v109, 2, v109
	ds_bpermute_b32 v109, v109, v98
	v_cmp_lt_i32_e32 vcc, v105, v100
	s_waitcnt lgkmcnt(0)
	v_add_f32_e32 v98, v98, v109
	v_cndmask_b32_e32 v109, v99, v105, vcc
	v_lshlrev_b32_e32 v109, 2, v109
	ds_bpermute_b32 v109, v109, v98
	v_cmp_lt_i32_e32 vcc, v106, v100
	s_waitcnt lgkmcnt(0)
	v_add_f32_e32 v98, v98, v109
	v_cndmask_b32_e32 v109, v99, v106, vcc
	v_lshlrev_b32_e32 v109, 2, v109
	ds_bpermute_b32 v109, v109, v98
	s_waitcnt lgkmcnt(0)
	v_add_f32_e32 v98, v98, v109
	v_fmamk_f32 v98, v98, 0x39800000, v107
	v_mul_f32_e32 v109, 0x4f800000, v98
	v_cmp_gt_f32_e32 vcc, s27, v98
	s_nop 1
	v_cndmask_b32_e32 v98, v98, v109, vcc
	v_sqrt_f32_e32 v109, v98
	s_nop 0
	v_add_u32_e32 v114, -1, v109
	v_fma_f32 v115, -v114, v109, v98
	v_cmp_ge_f32_e64 s[4:5], 0, v115
	v_add_u32_e32 v115, 1, v109
	s_nop 0
	v_cndmask_b32_e64 v114, v109, v114, s[4:5]
	v_fma_f32 v109, -v115, v109, v98
	v_cmp_lt_f32_e64 s[4:5], 0, v109
	s_nop 1
	v_cndmask_b32_e64 v109, v114, v115, s[4:5]
	v_mul_f32_e32 v114, 0x37800000, v109
	v_cndmask_b32_e32 v109, v109, v114, vcc
	v_cmp_class_f32_e32 vcc, v98, v108
	s_nop 1
	v_cndmask_b32_e32 v98, v109, v98, vcc
	v_div_scale_f32 v109, s[4:5], v98, v98, 1.0
	v_rcp_f32_e32 v114, v109
	s_add_u32 s4, s20, s30
	s_addc_u32 s5, s21, s31
	s_add_u32 s10, s10, s68
	v_fma_f32 v115, -v109, v114, 1.0
	v_fmac_f32_e32 v114, v115, v114
	v_div_scale_f32 v115, vcc, 1.0, v98, 1.0
	v_mul_f32_e32 v116, v115, v114
	v_fma_f32 v117, -v109, v116, v115
	v_fmac_f32_e32 v116, v117, v114
	v_fma_f32 v109, -v109, v116, v115
	v_div_fmas_f32 v109, v109, v114, v116
	v_div_fixup_f32 v98, v109, v98, 1.0
	v_pk_mul_f32 v[62:63], v[62:63], v[98:99] op_sel_hi:[1,0]
	v_mov_b32_e32 v109, 0
	s_waitcnt vmcnt(0)
	v_pk_mul_f32 v[62:63], v[110:111], v[62:63]
	v_pk_mul_f32 v[64:65], v[64:65], v[98:99] op_sel_hi:[1,0]
	v_cvt_pk_fp8_f32 v109, v62, v63
	v_pk_mul_f32 v[64:65], v[112:113], v[64:65]
	v_cvt_pk_bf16_f32 v110, v62, v63
	v_cvt_pk_bf16_f32 v111, v64, v65
	v_cvt_pk_fp8_f32 v109, v64, v65 op_sel:[0,0,1]
	global_store_dwordx2 v94, v[110:111], s[22:23]
	v_lshl_add_u64 v[110:111], s[4:5], 0, v[96:97]
	v_add_co_u32_e32 v62, vcc, s28, v110
	v_pk_mul_f32 v[58:59], v[58:59], v[98:99] op_sel_hi:[1,0]
	s_nop 0
	v_addc_co_u32_e32 v63, vcc, 0, v111, vcc
	global_store_dword v[62:63], v109, off
	global_load_dwordx4 v[62:65], v[68:69], off offset:1024
	v_mov_b32_e32 v109, 0
	v_pk_mul_f32 v[60:61], v[60:61], v[98:99] op_sel_hi:[1,0]
	v_pk_mul_f32 v[54:55], v[54:55], v[98:99] op_sel_hi:[1,0]
	v_pk_mul_f32 v[56:57], v[56:57], v[98:99] op_sel_hi:[1,0]
	v_pk_mul_f32 v[42:43], v[42:43], v[98:99] op_sel_hi:[1,0]
	v_pk_mul_f32 v[44:45], v[44:45], v[98:99] op_sel_hi:[1,0]
	v_pk_mul_f32 v[50:51], v[50:51], v[98:99] op_sel_hi:[1,0]
	v_pk_mul_f32 v[46:47], v[46:47], v[98:99] op_sel_hi:[1,0]
	v_pk_mul_f32 v[34:35], v[34:35], v[98:99] op_sel_hi:[1,0]
	v_pk_mul_f32 v[36:37], v[36:37], v[98:99] op_sel_hi:[1,0]
	v_pk_mul_f32 v[38:39], v[38:39], v[98:99] op_sel_hi:[1,0]
	v_pk_mul_f32 v[30:31], v[30:31], v[98:99] op_sel_hi:[1,0]
	v_pk_mul_f32 v[32:33], v[32:33], v[98:99] op_sel_hi:[1,0]
	v_pk_mul_f32 v[22:23], v[22:23], v[98:99] op_sel_hi:[1,0]
	v_pk_mul_f32 v[24:25], v[24:25], v[98:99] op_sel_hi:[1,0]
	v_pk_mul_f32 v[26:27], v[26:27], v[98:99] op_sel_hi:[1,0]
	v_pk_mul_f32 v[18:19], v[18:19], v[98:99] op_sel_hi:[1,0]
	v_pk_mul_f32 v[20:21], v[20:21], v[98:99] op_sel_hi:[1,0]
	v_pk_mul_f32 v[10:11], v[10:11], v[98:99] op_sel_hi:[1,0]
	v_pk_mul_f32 v[12:13], v[12:13], v[98:99] op_sel_hi:[1,0]
	v_pk_mul_f32 v[14:15], v[14:15], v[98:99] op_sel_hi:[1,0]
	v_pk_mul_f32 v[6:7], v[6:7], v[98:99] op_sel_hi:[1,0]
	v_pk_mul_f32 v[8:9], v[8:9], v[98:99] op_sel_hi:[1,0]
	v_pk_mul_f32 v[2:3], v[2:3], v[98:99] op_sel_hi:[1,0]
	v_pk_mul_f32 v[4:5], v[4:5], v[98:99] op_sel_hi:[1,0]
	s_addc_u32 s11, s11, s69
	s_add_u32 s8, s8, s12
	s_addc_u32 s9, s9, s13
	s_cmpk_gt_i32 s10, 0x5fff
	s_waitcnt vmcnt(0)
	v_pk_mul_f32 v[62:63], v[62:63], v[58:59]
	s_nop 0
	v_cvt_pk_fp8_f32 v109, v62, v63
	v_pk_mul_f32 v[60:61], v[64:65], v[60:61]
	v_cvt_pk_bf16_f32 v62, v62, v63
	v_cvt_pk_bf16_f32 v63, v60, v61
	v_cvt_pk_fp8_f32 v109, v60, v61 op_sel:[0,0,1]
	v_lshl_add_u64 v[58:59], v[110:111], 0, s[16:17]
	global_store_dwordx2 v94, v[62:63], s[22:23] offset:512
	global_store_dword v[58:59], v109, off offset:256
	global_load_dwordx4 v[60:63], v[68:69], off offset:2048
	v_mov_b32_e32 v64, 0
	s_waitcnt vmcnt(0)
	v_pk_mul_f32 v[54:55], v[54:55], v[60:61]
	s_nop 0
	v_cvt_pk_fp8_f32 v64, v54, v55
	v_pk_mul_f32 v[56:57], v[56:57], v[62:63]
	v_cvt_pk_bf16_f32 v54, v54, v55
	v_cvt_pk_bf16_f32 v55, v56, v57
	v_cvt_pk_fp8_f32 v64, v56, v57 op_sel:[0,0,1]
	global_store_dwordx2 v94, v[54:55], s[22:23] offset:1024
	global_store_dword v[58:59], v64, off offset:512
	global_load_dwordx4 v[54:57], v[68:69], off offset:3072
	v_mov_b32_e32 v60, 0
	s_waitcnt vmcnt(0)
	v_pk_mul_f32 v[42:43], v[42:43], v[54:55]
	s_nop 0
	v_cvt_pk_fp8_f32 v60, v42, v43
	v_pk_mul_f32 v[44:45], v[44:45], v[56:57]
	v_cvt_pk_bf16_f32 v42, v42, v43
	v_cvt_pk_bf16_f32 v43, v44, v45
	v_cvt_pk_fp8_f32 v60, v44, v45 op_sel:[0,0,1]
	global_store_dwordx2 v94, v[42:43], s[22:23] offset:1536
	global_store_dword v[58:59], v60, off offset:768
	global_load_dwordx4 v[42:45], v[70:71], off
	v_mov_b32_e32 v54, 0
	s_waitcnt vmcnt(0)
; #define GAS __attribute__((address_space(1)))
; __device__ __forceinline__ unsigned pk2(float lo, float hi) { return pg8::cvt_pk_bf16(lo, hi); }
; __device__ __forceinline__ unsigned pk4_fp8(float a, float b, float c, float d) { unsigned w = 0u; w = __builtin_amdgcn_cvt_pk_fp8_f32(a, b, w, false); w = __builtin_amdgcn_cvt_pk_fp8_f32(c, d, w, true); return w; }
; __device__ __forceinline__ void rms_row_to_bf16(const float* xrow, const float* g, bf16* orow, int lane, unsigned char* o8row = nullptr) {
;     ...
; #pragma unroll
;     for (int j = 0; j < 16; ++j) { const f32x4 gg = gr[64 * j]; const float a = v[j].x * inv * gg.x, b = v[j].y * inv * gg.y, c = v[j].z * inv * gg.z, d = v[j].w * inv * gg.w;
;         v2u w; w.x = pk2(a, b); w.y = pk2(c, d); o8[64 * j] = w;
;         if (o8row) ((GAS unsigned*)o8row)[lane + 64 * j] = pk4_fp8(a, b, c, d); }
	v_pk_mul_f32 v[42:43], v[50:51], v[42:43]
	s_nop 0
	v_cvt_pk_fp8_f32 v54, v42, v43
	v_pk_mul_f32 v[50:51], v[52:53], v[98:99] op_sel_hi:[1,0]
	v_cvt_pk_bf16_f32 v42, v42, v43
	v_pk_mul_f32 v[44:45], v[50:51], v[44:45]
	v_mov_b32_e32 v50, 0
	v_cvt_pk_fp8_f32 v54, v44, v45 op_sel:[0,0,1]
	v_cvt_pk_bf16_f32 v43, v44, v45
	global_store_dwordx2 v94, v[42:43], s[22:23] offset:2048
	global_store_dword v[58:59], v54, off offset:1024
	global_load_dwordx4 v[42:45], v[72:73], off
	s_waitcnt vmcnt(0)
	v_pk_mul_f32 v[42:43], v[46:47], v[42:43]
	s_nop 0
	v_cvt_pk_fp8_f32 v50, v42, v43
	v_pk_mul_f32 v[46:47], v[48:49], v[98:99] op_sel_hi:[1,0]
	v_cvt_pk_bf16_f32 v42, v42, v43
	v_pk_mul_f32 v[44:45], v[46:47], v[44:45]
	v_mov_b32_e32 v46, 0
	v_cvt_pk_fp8_f32 v50, v44, v45 op_sel:[0,0,1]
	v_cvt_pk_bf16_f32 v43, v44, v45
	global_store_dwordx2 v94, v[42:43], s[22:23] offset:2560
	global_store_dword v[58:59], v50, off offset:1280
	global_load_dwordx4 v[42:45], v[74:75], off
	s_waitcnt vmcnt(0)
	v_pk_mul_f32 v[34:35], v[34:35], v[42:43]
	s_nop 0
	v_cvt_pk_fp8_f32 v46, v34, v35
	v_pk_mul_f32 v[36:37], v[36:37], v[44:45]
	v_cvt_pk_bf16_f32 v34, v34, v35
	v_cvt_pk_bf16_f32 v35, v36, v37
	v_cvt_pk_fp8_f32 v46, v36, v37 op_sel:[0,0,1]
	global_store_dwordx2 v94, v[34:35], s[22:23] offset:3072
	global_store_dword v[58:59], v46, off offset:1536
	global_load_dwordx4 v[34:37], v[76:77], off
	v_mov_b32_e32 v42, 0
	s_waitcnt vmcnt(0)
	v_pk_mul_f32 v[34:35], v[38:39], v[34:35]
	s_nop 0
	v_cvt_pk_fp8_f32 v42, v34, v35
	v_pk_mul_f32 v[38:39], v[40:41], v[98:99] op_sel_hi:[1,0]
	v_cvt_pk_bf16_f32 v34, v34, v35
	v_pk_mul_f32 v[36:37], v[38:39], v[36:37]
	v_mov_b32_e32 v40, 0
	v_cvt_pk_fp8_f32 v42, v36, v37 op_sel:[0,0,1]
	v_cvt_pk_bf16_f32 v35, v36, v37
	global_store_dwordx2 v94, v[34:35], s[22:23] offset:3584
	global_store_dword v[58:59], v42, off offset:1792
	global_load_dwordx4 v[34:37], v[78:79], off
	v_lshl_add_u64 v[38:39], s[22:23], 0, v[94:95]
	s_waitcnt vmcnt(0)
	v_pk_mul_f32 v[30:31], v[30:31], v[34:35]
	s_nop 0
	v_cvt_pk_fp8_f32 v40, v30, v31
	v_pk_mul_f32 v[32:33], v[32:33], v[36:37]
	v_add_co_u32_e32 v34, vcc, s24, v38
	v_cvt_pk_fp8_f32 v40, v32, v33 op_sel:[0,0,1]
	s_nop 0
	v_addc_co_u32_e32 v35, vcc, 0, v39, vcc
	v_cvt_pk_bf16_f32 v30, v30, v31
	v_cvt_pk_bf16_f32 v31, v32, v33
	global_store_dwordx2 v[34:35], v[30:31], off
	global_store_dword v[58:59], v40, off offset:2048
	global_load_dwordx4 v[30:33], v[80:81], off
	v_mov_b32_e32 v36, 0
	s_waitcnt vmcnt(0)
	v_pk_mul_f32 v[22:23], v[22:23], v[30:31]
	s_nop 0
	v_cvt_pk_fp8_f32 v36, v22, v23
	v_pk_mul_f32 v[24:25], v[24:25], v[32:33]
	v_cvt_pk_bf16_f32 v22, v22, v23
	v_cvt_pk_bf16_f32 v23, v24, v25
	v_cvt_pk_fp8_f32 v36, v24, v25 op_sel:[0,0,1]
	global_store_dwordx2 v[34:35], v[22:23], off offset:512
	global_store_dword v[58:59], v36, off offset:2304
	global_load_dwordx4 v[22:25], v[82:83], off
	v_mov_b32_e32 v30, 0
	s_waitcnt vmcnt(0)
	v_pk_mul_f32 v[22:23], v[26:27], v[22:23]
	s_nop 0
	v_cvt_pk_fp8_f32 v30, v22, v23
	v_pk_mul_f32 v[26:27], v[28:29], v[98:99] op_sel_hi:[1,0]
	v_cvt_pk_bf16_f32 v22, v22, v23
	v_pk_mul_f32 v[24:25], v[26:27], v[24:25]
	v_mov_b32_e32 v26, 0
	v_cvt_pk_fp8_f32 v30, v24, v25 op_sel:[0,0,1]
	v_cvt_pk_bf16_f32 v23, v24, v25
	global_store_dwordx2 v[34:35], v[22:23], off offset:1024
	global_store_dword v[58:59], v30, off offset:2560
	global_load_dwordx4 v[22:25], v[84:85], off
	s_waitcnt vmcnt(0)
	v_pk_mul_f32 v[18:19], v[18:19], v[22:23]
	s_nop 0
	v_cvt_pk_fp8_f32 v26, v18, v19
	v_pk_mul_f32 v[20:21], v[20:21], v[24:25]
	v_cvt_pk_bf16_f32 v18, v18, v19
	v_cvt_pk_bf16_f32 v19, v20, v21
	v_cvt_pk_fp8_f32 v26, v20, v21 op_sel:[0,0,1]
	global_store_dwordx2 v[34:35], v[18:19], off offset:1536
	global_store_dword v[58:59], v26, off offset:2816
	global_load_dwordx4 v[18:21], v[86:87], off
	v_mov_b32_e32 v22, 0
	s_waitcnt vmcnt(0)
	v_pk_mul_f32 v[10:11], v[10:11], v[18:19]
	s_nop 0
	v_cvt_pk_fp8_f32 v22, v10, v11
	v_pk_mul_f32 v[12:13], v[12:13], v[20:21]
	v_cvt_pk_bf16_f32 v10, v10, v11
	v_cvt_pk_bf16_f32 v11, v12, v13
	v_cvt_pk_fp8_f32 v22, v12, v13 op_sel:[0,0,1]
	global_store_dwordx2 v[34:35], v[10:11], off offset:2048
	global_store_dword v[58:59], v22, off offset:3072
	global_load_dwordx4 v[10:13], v[88:89], off
	v_mov_b32_e32 v18, 0
	s_waitcnt vmcnt(0)
	v_pk_mul_f32 v[10:11], v[14:15], v[10:11]
	s_nop 0
	v_cvt_pk_fp8_f32 v18, v10, v11
	v_pk_mul_f32 v[14:15], v[16:17], v[98:99] op_sel_hi:[1,0]
	v_cvt_pk_bf16_f32 v10, v10, v11
	v_pk_mul_f32 v[12:13], v[14:15], v[12:13]
	v_mov_b32_e32 v14, 0
	v_cvt_pk_fp8_f32 v18, v12, v13 op_sel:[0,0,1]
	v_cvt_pk_bf16_f32 v11, v12, v13
	global_store_dwordx2 v[34:35], v[10:11], off offset:2560
	global_store_dword v[58:59], v18, off offset:3328
	global_load_dwordx4 v[10:13], v[90:91], off
	s_waitcnt vmcnt(0)
	v_pk_mul_f32 v[6:7], v[6:7], v[10:11]
	s_nop 0
	v_cvt_pk_fp8_f32 v14, v6, v7
	v_pk_mul_f32 v[8:9], v[8:9], v[12:13]
	v_cvt_pk_bf16_f32 v6, v6, v7
	v_cvt_pk_bf16_f32 v7, v8, v9
	v_cvt_pk_fp8_f32 v14, v8, v9 op_sel:[0,0,1]
	global_store_dwordx2 v[34:35], v[6:7], off offset:3072
	global_store_dword v[58:59], v14, off offset:3584
	global_load_dwordx4 v[6:9], v[92:93], off
	v_mov_b32_e32 v10, 0
	s_waitcnt vmcnt(0)
	v_pk_mul_f32 v[2:3], v[2:3], v[6:7]
	s_nop 0
	v_cvt_pk_fp8_f32 v10, v2, v3
	v_pk_mul_f32 v[4:5], v[4:5], v[8:9]
	v_cvt_pk_bf16_f32 v2, v2, v3
	v_cvt_pk_bf16_f32 v3, v4, v5
	v_cvt_pk_fp8_f32 v10, v4, v5 op_sel:[0,0,1]
	global_store_dwordx2 v[34:35], v[2:3], off offset:3584
	global_store_dword v[58:59], v10, off offset:3840
	s_cbranch_scc1 .LBB0_75

; #define GAS __attribute__((address_space(1)))
; __device__ __forceinline__ float bflo(unsigned w) { return __uint_as_float(w << 16); }
; __device__ __forceinline__ float bfhi(unsigned w) { return __uint_as_float(w & 0xffff0000u); }
; __device__ __forceinline__ void rms_row_bf16_to_f32(const bf16* hrow, const float* g, float* orow, int lane) {
;     const GAS v4u* hr = (const GAS v4u*)hrow + lane;
;     v4u v[8]; float s = 0.f;
; #pragma unroll
;     for (int j = 0; j < 8; ++j) { v[j] = hr[64 * j];
;         const float a0 = bflo(v[j].x), a1 = bfhi(v[j].x), a2 = bflo(v[j].y), a3 = bfhi(v[j].y), a4 = bflo(v[j].z), a5 = bfhi(v[j].z), a6 = bflo(v[j].w), a7 = bfhi(v[j].w);
;         s += ((a0 * a0 + a1 * a1) + (a2 * a2 + a3 * a3)) + ((a4 * a4 + a5 * a5) + (a6 * a6 + a7 * a7)); }
.LBB0_1131:
	v_add_co_u32_e32 v62, vcc, s11, v40
	global_load_dwordx4 v[8:11], v24, s[4:5] offset:1024
	global_load_dwordx4 v[16:19], v24, s[4:5] offset:2048
	global_load_dwordx4 v[12:15], v24, s[4:5]
	global_load_dwordx4 v[20:23], v24, s[4:5] offset:3072
	v_lshl_add_u64 v[42:43], s[4:5], 0, v[24:25]
	v_addc_co_u32_e32 v63, vcc, -1, v41, vcc
	v_add_co_u32_e32 v46, vcc, s10, v42
	global_load_dwordx4 v[0:3], v[26:27], off offset:16
	global_load_dwordx4 v[4:7], v[26:27], off
	v_addc_co_u32_e32 v47, vcc, 0, v43, vcc
	global_load_dwordx4 v[42:45], v[46:47], off
	global_load_dwordx4 v[76:79], v[46:47], off offset:1024
	global_load_dwordx4 v[80:83], v[46:47], off offset:2048
	global_load_dwordx4 v[84:87], v[46:47], off offset:3072
	s_add_i32 s2, s2, s68
	s_add_u32 s4, s4, s6
	s_addc_u32 s5, s5, s7
	s_cmpk_gt_i32 s2, 0x5fff
	s_waitcnt vmcnt(0)
	v_and_b32_e32 v91, 0xffff0000, v9
	v_and_b32_e32 v90, 0xffff0000, v8
	v_and_b32_e32 v105, 0xffff0000, v14
	v_and_b32_e32 v107, 0xffff0000, v15
	v_and_b32_e32 v109, 0xffff0000, v12
	v_and_b32_e32 v111, 0xffff0000, v13
	v_and_b32_e32 v95, 0xffff0000, v11
	v_and_b32_e32 v94, 0xffff0000, v10
	v_lshlrev_b32_e32 v104, 16, v14
	v_lshlrev_b32_e32 v106, 16, v15
	v_lshlrev_b32_e32 v108, 16, v12
	v_lshlrev_b32_e32 v110, 16, v13
	v_mov_b32_e32 v116, v107
	v_mov_b32_e32 v117, v105
	v_mov_b32_e32 v120, v109
	v_mov_b32_e32 v121, v111
	v_lshlrev_b32_e32 v89, 16, v9
	v_lshlrev_b32_e32 v88, 16, v8
	v_lshlrev_b32_e32 v93, 16, v11
	v_lshlrev_b32_e32 v92, 16, v10
	v_and_b32_e32 v97, 0xffff0000, v16
	v_and_b32_e32 v99, 0xffff0000, v17
	v_and_b32_e32 v101, 0xffff0000, v18
	v_and_b32_e32 v103, 0xffff0000, v19
	v_pk_mul_f32 v[8:9], v[90:91], v[90:91]
	v_pk_mul_f32 v[10:11], v[94:95], v[94:95]
	v_mov_b32_e32 v114, v106
	v_mov_b32_e32 v115, v104
	v_mov_b32_e32 v118, v108
	v_mov_b32_e32 v119, v110
	v_lshlrev_b32_e32 v53, 16, v44
	v_lshlrev_b32_e32 v52, 16, v43
	v_and_b32_e32 v51, 0xffff0000, v44
	v_and_b32_e32 v50, 0xffff0000, v43
	v_lshlrev_b32_e32 v57, 16, v45
	v_lshlrev_b32_e32 v56, 16, v42
	v_and_b32_e32 v55, 0xffff0000, v45
	v_and_b32_e32 v54, 0xffff0000, v42
	v_lshlrev_b32_e32 v47, 16, v77
	v_lshlrev_b32_e32 v46, 16, v76
	v_and_b32_e32 v45, 0xffff0000, v77
	v_and_b32_e32 v44, 0xffff0000, v76
	v_lshlrev_b32_e32 v49, 16, v79
	v_lshlrev_b32_e32 v48, 16, v78
	v_and_b32_e32 v43, 0xffff0000, v79
	v_and_b32_e32 v42, 0xffff0000, v78
	v_pk_mul_f32 v[76:77], v[116:117], v[116:117]
	v_pk_mul_f32 v[78:79], v[120:121], v[120:121]
	v_lshlrev_b32_e32 v96, 16, v16
	v_lshlrev_b32_e32 v98, 16, v17
	v_lshlrev_b32_e32 v100, 16, v18
	v_lshlrev_b32_e32 v102, 16, v19
	v_lshlrev_b32_e32 v58, 16, v22
	v_and_b32_e32 v59, 0xffff0000, v22
	v_lshlrev_b32_e32 v60, 16, v23
	v_and_b32_e32 v61, 0xffff0000, v23
	v_lshlrev_b32_e32 v64, 16, v20
	v_and_b32_e32 v65, 0xffff0000, v20
	v_lshlrev_b32_e32 v112, 16, v21
	v_and_b32_e32 v113, 0xffff0000, v21
	v_mul_f32_e32 v12, v97, v97
	v_mul_f32_e32 v14, v99, v99
	v_mul_f32_e32 v16, v101, v101
	v_mul_f32_e32 v18, v103, v103
	v_pk_fma_f32 v[130:131], v[88:89], v[88:89], v[8:9]
	v_pk_fma_f32 v[132:133], v[92:93], v[92:93], v[10:11]
	v_pk_fma_f32 v[76:77], v[114:115], v[114:115], v[76:77]
	v_pk_fma_f32 v[78:79], v[118:119], v[118:119], v[78:79]
	v_pk_mul_f32 v[122:123], v[58:59], v[58:59]
	v_pk_mul_f32 v[124:125], v[60:61], v[60:61]
	v_pk_mul_f32 v[126:127], v[64:65], v[64:65]
	v_pk_mul_f32 v[128:129], v[112:113], v[112:113]
	v_pk_fma_f32 v[134:135], v[96:97], v[96:97], v[12:13] op_sel_hi:[1,1,0]
	v_pk_fma_f32 v[136:137], v[98:99], v[98:99], v[14:15] op_sel_hi:[1,1,0]
	v_pk_fma_f32 v[138:139], v[100:101], v[100:101], v[16:17] op_sel_hi:[1,1,0]
	v_pk_fma_f32 v[140:141], v[102:103], v[102:103], v[18:19] op_sel_hi:[1,1,0]
	v_lshlrev_b32_e32 v18, 16, v80
	v_and_b32_e32 v19, 0xffff0000, v80
	v_lshlrev_b32_e32 v22, 16, v81
	v_and_b32_e32 v23, 0xffff0000, v81
	v_lshlrev_b32_e32 v16, 16, v82
	v_and_b32_e32 v17, 0xffff0000, v82
	v_lshlrev_b32_e32 v20, 16, v83
	v_and_b32_e32 v21, 0xffff0000, v83
	v_pk_add_f32 v[80:81], v[130:131], v[130:131] op_sel:[0,1] op_sel_hi:[1,0]
	v_pk_add_f32 v[82:83], v[132:133], v[132:133] op_sel:[1,0] op_sel_hi:[0,1]
	v_pk_add_f32 v[76:77], v[76:77], v[76:77] op_sel:[0,1] op_sel_hi:[1,0]
	v_pk_add_f32 v[78:79], v[78:79], v[78:79] op_sel:[0,1] op_sel_hi:[1,0]
	v_lshlrev_b32_e32 v8, 16, v86
	v_and_b32_e32 v9, 0xffff0000, v86
	v_lshlrev_b32_e32 v10, 16, v87
	v_and_b32_e32 v11, 0xffff0000, v87
	v_lshlrev_b32_e32 v12, 16, v84
	v_and_b32_e32 v13, 0xffff0000, v84
	v_lshlrev_b32_e32 v14, 16, v85
	v_and_b32_e32 v15, 0xffff0000, v85
	v_pk_mul_f32 v[84:85], v[50:51], v[50:51]
	v_pk_mul_f32 v[86:87], v[54:55], v[54:55]
	v_pk_mul_f32 v[116:117], v[44:45], v[44:45]
	v_pk_mul_f32 v[120:121], v[42:43], v[42:43]
	v_mov_b32_e32 v141, v122
	v_mov_b32_e32 v139, v123
	v_mov_b32_e32 v135, v124
	v_mov_b32_e32 v137, v125
	v_mov_b32_e32 v81, v128
	v_mov_b32_e32 v83, v129
	v_mov_b32_e32 v79, v126
	v_mov_b32_e32 v77, v127
	v_pk_fma_f32 v[84:85], v[52:53], v[52:53], v[84:85]
	v_pk_fma_f32 v[86:87], v[56:57], v[56:57], v[86:87]
	v_pk_fma_f32 v[116:117], v[46:47], v[46:47], v[116:117]
	v_pk_fma_f32 v[120:121], v[48:49], v[48:49], v[120:121]
	v_pk_add_f32 v[138:139], v[140:141], v[138:139]
	v_pk_add_f32 v[134:135], v[134:135], v[136:137]
	v_pk_add_f32 v[80:81], v[80:81], v[82:83]
	v_pk_add_f32 v[76:77], v[78:79], v[76:77]
	v_pk_add_f32 v[84:85], v[86:87], v[84:85]
	v_pk_add_f32 v[86:87], v[116:117], v[116:117] op_sel:[0,1] op_sel_hi:[1,0]
	v_pk_add_f32 v[116:117], v[120:121], v[120:121] op_sel:[1,0] op_sel_hi:[0,1]
	v_pk_add_f32 v[120:121], v[134:135], v[138:139]
	v_pk_add_f32 v[76:77], v[76:77], v[80:81]
	v_mul_f32_e32 v66, v19, v19
	v_mul_f32_e32 v130, v23, v23
	v_mul_f32_e32 v132, v17, v17
	v_mul_f32_e32 v142, v21, v21
	v_pk_add_f32 v[76:77], v[76:77], v[120:121]
	v_pk_mul_f32 v[114:115], v[8:9], v[8:9]
	v_pk_mul_f32 v[118:119], v[10:11], v[10:11]
	v_pk_mul_f32 v[122:123], v[12:13], v[12:13]
	v_pk_mul_f32 v[124:125], v[14:15], v[14:15]
	v_pk_fma_f32 v[144:145], v[18:19], v[18:19], v[66:67] op_sel_hi:[1,1,0]
	v_pk_fma_f32 v[130:131], v[22:23], v[22:23], v[130:131] op_sel_hi:[1,1,0]
	v_pk_fma_f32 v[132:133], v[16:17], v[16:17], v[132:133] op_sel_hi:[1,1,0]
	v_pk_fma_f32 v[142:143], v[20:21], v[20:21], v[142:143] op_sel_hi:[1,1,0]
	v_pk_add_f32 v[82:83], v[84:85], v[84:85] op_sel:[0,1] op_sel_hi:[1,0]
	v_pk_add_f32 v[76:77], v[76:77], v[76:77] op_sel:[0,1] op_sel_hi:[1,0]
	v_mov_b32_e32 v143, v114
	v_mov_b32_e32 v133, v115
	v_mov_b32_e32 v145, v118
	v_mov_b32_e32 v131, v119
	v_mov_b32_e32 v87, v124
	v_mov_b32_e32 v117, v125
	v_mov_b32_e32 v83, v123
	v_mov_b32_e32 v77, v122
	v_pk_add_f32 v[78:79], v[142:143], v[132:133]
	v_pk_add_f32 v[84:85], v[144:145], v[130:131]
	v_pk_add_f32 v[80:81], v[86:87], v[116:117]
	v_pk_add_f32 v[76:77], v[76:77], v[82:83]
	v_pk_add_f32 v[78:79], v[84:85], v[78:79]
	v_pk_add_f32 v[76:77], v[76:77], v[80:81]
	s_nop 0
	v_pk_add_f32 v[76:77], v[76:77], v[78:79]
	s_nop 0
	v_add_f32_e32 v66, v76, v77
	ds_bpermute_b32 v75, v67, v66
	s_waitcnt lgkmcnt(0)
; #define GAS __attribute__((address_space(1)))
; __device__ __forceinline__ float bflo(unsigned w) { return __uint_as_float(w << 16); }
; __device__ __forceinline__ float bfhi(unsigned w) { return __uint_as_float(w & 0xffff0000u); }
; __device__ __forceinline__ void rms_row_bf16_to_f32(const bf16* hrow, const float* g, float* orow, int lane) {
;     ...
;         s += ((a0 * a0 + a1 * a1) + (a2 * a2 + a3 * a3)) + ((a4 * a4 + a5 * a5) + (a6 * a6 + a7 * a7)); }
;     const float inv = 1.0f / sqrtf(wave_sum(s) * (1.f / DM) + EPS);
; #pragma unroll
;     for (int j = 0; j < 8; ++j) { const int c = 512 * j + 8 * lane; const f32x4 g0 = *(const GAS f32x4*)(g + c), g1 = *(const GAS f32x4*)(g + c + 4);
;         f32x4 o0, o1; o0.x = bflo(v[j].x) * inv * g0.x; o0.y = bfhi(v[j].x) * inv * g0.y; o0.z = bflo(v[j].y) * inv * g0.z; o0.w = bfhi(v[j].y) * inv * g0.w;
;         o1.x = bflo(v[j].z) * inv * g1.x; o1.y = bfhi(v[j].z) * inv * g1.y; o1.z = bflo(v[j].w) * inv * g1.z; o1.w = bfhi(v[j].w) * inv * g1.w;
;         *(GAS f32x4*)(orow + c) = o0; *(GAS f32x4*)(orow + c + 4) = o1; }
	v_add_f32_e32 v66, v66, v75
	ds_bpermute_b32 v75, v68, v66
	s_waitcnt lgkmcnt(0)
	v_add_f32_e32 v66, v66, v75
	ds_bpermute_b32 v75, v69, v66
	s_waitcnt lgkmcnt(0)
	v_add_f32_e32 v66, v66, v75
	ds_bpermute_b32 v75, v70, v66
	s_waitcnt lgkmcnt(0)
	v_add_f32_e32 v66, v66, v75
	ds_bpermute_b32 v75, v71, v66
	s_waitcnt lgkmcnt(0)
	v_add_f32_e32 v66, v66, v75
	ds_bpermute_b32 v75, v72, v66
	s_waitcnt lgkmcnt(0)
	v_add_f32_e32 v66, v66, v75
	v_fmamk_f32 v66, v66, 0x39800000, v73
	v_mul_f32_e32 v75, 0x4f800000, v66
	v_cmp_gt_f32_e32 vcc, s3, v66
	s_nop 1
	v_cndmask_b32_e32 v66, v66, v75, vcc
	v_sqrt_f32_e32 v75, v66
	s_nop 0
	v_add_u32_e32 v76, -1, v75
	v_add_u32_e32 v77, 1, v75
	v_fma_f32 v78, -v76, v75, v66
	v_fma_f32 v79, -v77, v75, v66
	v_cmp_ge_f32_e64 s[0:1], 0, v78
	s_nop 1
	v_cndmask_b32_e64 v75, v75, v76, s[0:1]
	v_cmp_lt_f32_e64 s[0:1], 0, v79
	s_nop 1
	v_cndmask_b32_e64 v75, v75, v77, s[0:1]
	v_mul_f32_e32 v76, 0x37800000, v75
	v_cndmask_b32_e32 v75, v75, v76, vcc
	v_cmp_class_f32_e32 vcc, v66, v74
	s_nop 1
	v_cndmask_b32_e32 v66, v75, v66, vcc
	v_div_scale_f32 v75, s[0:1], v66, v66, 1.0
	v_rcp_f32_e32 v77, v75
	v_div_scale_f32 v76, vcc, 1.0, v66, 1.0
	v_fma_f32 v78, -v75, v77, 1.0
	v_fmac_f32_e32 v77, v78, v77
	v_mul_f32_e32 v78, v76, v77
	v_fma_f32 v79, -v75, v78, v76
	v_fmac_f32_e32 v78, v79, v77
	v_fma_f32 v75, -v75, v78, v76
	v_div_fmas_f32 v75, v75, v77, v78
	v_div_fixup_f32 v66, v75, v66, 1.0
	v_pk_mul_f32 v[76:77], v[66:67], v[108:109] op_sel_hi:[0,1]
	v_pk_mul_f32 v[78:79], v[66:67], v[110:111] op_sel_hi:[0,1]
	v_pk_mul_f32 v[80:81], v[66:67], v[104:105] op_sel_hi:[0,1]
	v_pk_mul_f32 v[82:83], v[66:67], v[106:107] op_sel_hi:[0,1]
	v_pk_mul_f32 v[4:5], v[4:5], v[76:77]
	v_pk_mul_f32 v[6:7], v[6:7], v[78:79]
	v_pk_mul_f32 v[0:1], v[0:1], v[80:81]
	v_pk_mul_f32 v[2:3], v[2:3], v[82:83]
	global_store_dwordx4 v[62:63], v[4:7], off offset:-2064 nt
	global_store_dwordx4 v[62:63], v[0:3], off offset:-2048 nt
	global_load_dwordx4 v[0:3], v[26:27], off offset:2048
	s_nop 0
	global_load_dwordx4 v[4:7], v[26:27], off offset:2064
	v_mov_b32_e32 v78, v88
	v_mov_b32_e32 v79, v90
	v_mov_b32_e32 v90, v89
	v_mov_b32_e32 v80, v92
	v_mov_b32_e32 v81, v94
	v_mov_b32_e32 v94, v93
	v_pk_mul_f32 v[78:79], v[66:67], v[78:79] op_sel_hi:[0,1]
	v_pk_mul_f32 v[82:83], v[66:67], v[90:91] op_sel_hi:[0,1]
	v_add_co_u32_e32 v76, vcc, s12, v40
	v_pk_mul_f32 v[80:81], v[66:67], v[80:81] op_sel_hi:[0,1]
	v_pk_mul_f32 v[84:85], v[66:67], v[94:95] op_sel_hi:[0,1]
	v_addc_co_u32_e32 v77, vcc, -1, v41, vcc
	v_pk_mul_f32 v[64:65], v[66:67], v[64:65] op_sel_hi:[0,1]
	v_pk_mul_f32 v[60:61], v[66:67], v[60:61] op_sel_hi:[0,1]
	v_pk_mul_f32 v[58:59], v[66:67], v[58:59] op_sel_hi:[0,1]
	v_pk_mul_f32 v[22:23], v[66:67], v[22:23] op_sel_hi:[0,1]
	v_pk_mul_f32 v[18:19], v[66:67], v[18:19] op_sel_hi:[0,1]
	v_pk_mul_f32 v[20:21], v[66:67], v[20:21] op_sel_hi:[0,1]
	v_pk_mul_f32 v[16:17], v[66:67], v[16:17] op_sel_hi:[0,1]
	v_pk_mul_f32 v[14:15], v[66:67], v[14:15] op_sel_hi:[0,1]
	v_pk_mul_f32 v[12:13], v[66:67], v[12:13] op_sel_hi:[0,1]
	v_pk_mul_f32 v[10:11], v[66:67], v[10:11] op_sel_hi:[0,1]
	v_pk_mul_f32 v[8:9], v[66:67], v[8:9] op_sel_hi:[0,1]
	s_waitcnt vmcnt(1)
	v_pk_mul_f32 v[0:1], v[0:1], v[78:79]
	v_pk_mul_f32 v[2:3], v[2:3], v[82:83]
	s_waitcnt vmcnt(0)
	v_pk_mul_f32 v[4:5], v[4:5], v[80:81]
	v_pk_mul_f32 v[6:7], v[6:7], v[84:85]
	global_store_dwordx4 v[62:63], v[0:3], off offset:-16 nt
	global_store_dwordx4 v[76:77], v[4:7], off offset:-4096 nt
	global_load_dwordx4 v[0:3], v[28:29], off
	s_nop 0
	global_load_dwordx4 v[4:7], v[28:29], off offset:16
	v_pk_mul_f32 v[62:63], v[66:67], v[98:99] op_sel_hi:[0,1]
	v_pk_mul_f32 v[78:79], v[66:67], v[96:97] op_sel_hi:[0,1]
	v_pk_mul_f32 v[80:81], v[66:67], v[102:103] op_sel_hi:[0,1]
	v_pk_mul_f32 v[82:83], v[66:67], v[100:101] op_sel_hi:[0,1]
	s_waitcnt vmcnt(1)
; #define GAS __attribute__((address_space(1)))
; __device__ __forceinline__ float bflo(unsigned w) { return __uint_as_float(w << 16); }
; __device__ __forceinline__ float bfhi(unsigned w) { return __uint_as_float(w & 0xffff0000u); }
; __device__ __forceinline__ void rms_row_bf16_to_f32(const bf16* hrow, const float* g, float* orow, int lane) {
;     ...
;     for (int j = 0; j < 8; ++j) { const int c = 512 * j + 8 * lane; const f32x4 g0 = *(const GAS f32x4*)(g + c), g1 = *(const GAS f32x4*)(g + c + 4);
;         f32x4 o0, o1; o0.x = bflo(v[j].x) * inv * g0.x; o0.y = bfhi(v[j].x) * inv * g0.y; o0.z = bflo(v[j].y) * inv * g0.z; o0.w = bfhi(v[j].y) * inv * g0.w;
;         o1.x = bflo(v[j].z) * inv * g1.x; o1.y = bfhi(v[j].z) * inv * g1.y; o1.z = bflo(v[j].w) * inv * g1.z; o1.w = bfhi(v[j].w) * inv * g1.w;
;         *(GAS f32x4*)(orow + c) = o0; *(GAS f32x4*)(orow + c + 4) = o1; }
	v_pk_mul_f32 v[0:1], v[0:1], v[78:79]
	v_pk_mul_f32 v[2:3], v[2:3], v[62:63]
	s_waitcnt vmcnt(0)
	v_pk_mul_f32 v[4:5], v[82:83], v[4:5]
	v_pk_mul_f32 v[6:7], v[80:81], v[6:7]
	global_store_dwordx4 v[76:77], v[0:3], off offset:-2064 nt
	global_store_dwordx4 v[76:77], v[4:7], off offset:-2048 nt
	global_load_dwordx4 v[0:3], v[30:31], off
	s_nop 0
	global_load_dwordx4 v[4:7], v[30:31], off offset:16
	v_pk_mul_f32 v[62:63], v[66:67], v[112:113] op_sel_hi:[0,1]
	s_waitcnt vmcnt(1)
	v_pk_mul_f32 v[0:1], v[64:65], v[0:1]
	v_pk_mul_f32 v[2:3], v[62:63], v[2:3]
	s_waitcnt vmcnt(0)
	v_pk_mul_f32 v[4:5], v[58:59], v[4:5]
	v_pk_mul_f32 v[6:7], v[60:61], v[6:7]
	global_store_dwordx4 v[76:77], v[0:3], off offset:-16 nt
	global_store_dwordx4 v[76:77], v[4:7], off nt
	global_load_dwordx4 v[0:3], v[32:33], off
	s_nop 0
	global_load_dwordx4 v[4:7], v[32:33], off offset:16
	v_mov_b32_e32 v60, v56
	v_mov_b32_e32 v61, v54
	v_mov_b32_e32 v62, v52
	v_mov_b32_e32 v63, v50
	v_add_co_u32_e32 v58, vcc, s13, v40
	v_mov_b32_e32 v50, v53
	v_mov_b32_e32 v54, v57
	v_pk_mul_f32 v[52:53], v[66:67], v[60:61] op_sel_hi:[0,1]
	v_pk_mul_f32 v[56:57], v[66:67], v[62:63] op_sel_hi:[0,1]
	v_addc_co_u32_e32 v59, vcc, -1, v41, vcc
	v_pk_mul_f32 v[50:51], v[66:67], v[50:51] op_sel_hi:[0,1]
	v_pk_mul_f32 v[54:55], v[66:67], v[54:55] op_sel_hi:[0,1]
	s_waitcnt vmcnt(1)
	v_pk_mul_f32 v[0:1], v[52:53], v[0:1]
	v_pk_mul_f32 v[2:3], v[56:57], v[2:3]
	s_waitcnt vmcnt(0)
	v_pk_mul_f32 v[4:5], v[50:51], v[4:5]
	v_pk_mul_f32 v[6:7], v[54:55], v[6:7]
	global_store_dwordx4 v[58:59], v[0:3], off offset:-2064 nt
	global_store_dwordx4 v[58:59], v[4:7], off offset:-2048 nt
	global_load_dwordx4 v[0:3], v[34:35], off
	s_nop 0
	global_load_dwordx4 v[4:7], v[34:35], off offset:16
	v_mov_b32_e32 v50, v46
	v_mov_b32_e32 v51, v44
	v_mov_b32_e32 v44, v47
	v_mov_b32_e32 v46, v48
	v_mov_b32_e32 v47, v42
	v_mov_b32_e32 v42, v49
	v_pk_mul_f32 v[48:49], v[66:67], v[50:51] op_sel_hi:[0,1]
	v_pk_mul_f32 v[44:45], v[66:67], v[44:45] op_sel_hi:[0,1]
	v_pk_mul_f32 v[46:47], v[66:67], v[46:47] op_sel_hi:[0,1]
	v_pk_mul_f32 v[42:43], v[66:67], v[42:43] op_sel_hi:[0,1]
	s_waitcnt vmcnt(1)
	v_pk_mul_f32 v[0:1], v[48:49], v[0:1]
	v_pk_mul_f32 v[2:3], v[44:45], v[2:3]
	s_waitcnt vmcnt(0)
	v_pk_mul_f32 v[4:5], v[46:47], v[4:5]
	v_pk_mul_f32 v[6:7], v[42:43], v[6:7]
	global_store_dwordx4 v[58:59], v[0:3], off offset:-16 nt
	global_store_dwordx4 v[40:41], v[4:7], off offset:-4096 nt
	global_load_dwordx4 v[0:3], v[36:37], off
	s_nop 0
	global_load_dwordx4 v[4:7], v[36:37], off offset:16
	s_waitcnt vmcnt(1)
	v_pk_mul_f32 v[0:1], v[18:19], v[0:1]
	v_pk_mul_f32 v[2:3], v[22:23], v[2:3]
	s_waitcnt vmcnt(0)
	v_pk_mul_f32 v[4:5], v[16:17], v[4:5]
	v_pk_mul_f32 v[6:7], v[20:21], v[6:7]
	global_store_dwordx4 v[40:41], v[0:3], off offset:-2064 nt
	global_store_dwordx4 v[40:41], v[4:7], off offset:-2048 nt
	global_load_dwordx4 v[0:3], v[38:39], off
	s_nop 0
	global_load_dwordx4 v[4:7], v[38:39], off offset:16
	s_waitcnt vmcnt(1)
	v_pk_mul_f32 v[0:1], v[12:13], v[0:1]
	v_pk_mul_f32 v[2:3], v[14:15], v[2:3]
	s_waitcnt vmcnt(0)
	v_pk_mul_f32 v[4:5], v[8:9], v[4:5]
	v_pk_mul_f32 v[6:7], v[10:11], v[6:7]
	global_store_dwordx4 v[40:41], v[0:3], off offset:-16 nt
	global_store_dwordx4 v[40:41], v[4:7], off nt
	v_lshl_add_u64 v[40:41], v[40:41], 0, s[8:9]
	s_cbranch_scc0 .LBB0_1131
